# RWKV step: S.a and S.r_prev accumulated in single chains (2 fewer VALU per step)
# speedup vs baseline: 1.0061x; 1.0061x over previous
; DEVINL u16 f2bf(float a) { return (u16)(pk2(a, 0.f) & 0xffffu); }
; #define RW_STEP2(B) RW_STEP(B, WvA, XA, KrA, vhA, WvB, XB, KrB, vhB); RW_STEP((B) + 1, WvB, XB, KrB, vhB, WvA, XA, KrA, vhA)
; #define RW_STEP4(B) RW_STEP2(B); RW_STEP2((B) + 2)
; template <int DIR>
; DEVINL void rwkv_scan_dir(const Params& p, int task, int lane, int wave) {
;     ...
;     if (st > 0) { const int q0 = st - 16 + seg; yo[(long)(DIR ? (4095 - q0) : q0) * 1024] = f2bf(ykeep); }
;     RW_STEP(1, WvB, XB, KrB, vhB, WvA, XA, KrA, vhA);
;     RW_STEP2(2); RW_STEP4(4); RW_STEP4(8); RW_STEP4(12);
;     RW_STEP(16, WvA, XA, KrA, vhA, WvB, XB, KrB, vhB);
;     { const int q0 = st + seg; yo[(long)(DIR ? (4095 - q0) : q0) * 1024] = f2bf(ykeep); }
.Lrw_ready_d0:
	s_add_u32 s3, s40, s41
	s_and_b32 s3, s3, 0x1ffff
	s_add_u32 s3, s3, 16
	s_mov_b32 m0, s3
	s_nop 0
	global_load_lds_dwordx4 v5, s[10:11] offset:0
	global_load_lds_dwordx4 v5, s[10:11] offset:1024
	global_load_lds_dwordx4 v5, s[10:11] offset:2048
	global_load_lds_dwordx4 v5, s[10:11] offset:3072
	s_add_u32 s10, s10, 0x4000
	s_addc_u32 s11, s11, 0
	s_add_u32 s41, s41, 0x4000
	s_and_b32 s41, s41, 0x1ffff
	ds_read_b64 v[72:73], v6 offset:2064
	ds_read_b128 v[74:77], v6 offset:2320
	ds_read_b128 v[78:81], v6 offset:2576
	ds_read_u16 v82, v7 offset:2064
	v_fma_mix_f32 v14, v10, v26, 0 op_sel:[0,0,0] op_sel_hi:[0,1,0]
	v_fma_mix_f32 v63, v10, v92, 0 op_sel:[0,0,0] op_sel_hi:[0,1,0]
	v_fma_mix_f32 v14, v11, v26, v14 op_sel:[0,1,0] op_sel_hi:[0,1,0]
	v_fma_mix_f32 v63, v11, v92, v63 op_sel:[0,1,0] op_sel_hi:[0,1,0]
	v_fma_mix_f32 v14, v12, v27, v14 op_sel:[0,0,0] op_sel_hi:[0,1,0]
	v_fma_mix_f32 v63, v12, v93, v63 op_sel:[0,0,0] op_sel_hi:[0,1,0]
	v_fma_mix_f32 v14, v13, v27, v14 op_sel:[0,1,0] op_sel_hi:[0,1,0]
	v_fma_mix_f32 v16, v10, v24, 0 op_sel:[0,0,0] op_sel_hi:[0,1,0]
	v_fma_mix_f32 v17, v11, v24, 0 op_sel:[0,1,0] op_sel_hi:[0,1,0]
	v_add_f32_dpp v20, v14, v14 quad_perm:[1,0,3,2] row_mask:0xf bank_mask:0xf bound_ctrl:1
	v_fma_mix_f32 v63, v13, v93, v63 op_sel:[0,1,0] op_sel_hi:[0,1,0]
	v_fma_mix_f32 v18, v12, v25, 0 op_sel:[0,0,0] op_sel_hi:[0,1,0]
	v_add_f32_dpp v20, v20, v20 quad_perm:[2,3,0,1] row_mask:0xf bank_mask:0xf bound_ctrl:1
	v_fma_mix_f32 v19, v13, v25, 0 op_sel:[0,1,0] op_sel_hi:[0,1,0]
	v_fma_mix_f32 v16, v34, v30, v16 op_sel:[0,0,0] op_sel_hi:[1,1,0]
	v_add_f32_dpp v20, v20, v20 row_half_mirror row_mask:0xf bank_mask:0xf bound_ctrl:1
	v_fma_mix_f32 v17, v34, v30, v17 op_sel:[0,1,0] op_sel_hi:[1,1,0]
	v_fma_mix_f32 v18, v34, v31, v18 op_sel:[0,0,0] op_sel_hi:[1,1,0]
	v_add_f32_dpp v20, v20, v20 row_mirror row_mask:0xf bank_mask:0xf bound_ctrl:1
	v_fma_mix_f32 v19, v34, v31, v19 op_sel:[0,1,0] op_sel_hi:[1,1,0]
	v_fma_mix_f32 v10, v20, v28, v16 op_sel:[0,0,0] op_sel_hi:[0,1,0]
	v_fma_mix_f32 v11, v20, v28, v17 op_sel:[0,1,0] op_sel_hi:[0,1,0]
	v_fma_mix_f32 v12, v20, v29, v18 op_sel:[0,0,0] op_sel_hi:[0,1,0]
	v_fma_mix_f32 v13, v20, v29, v19 op_sel:[0,1,0] op_sel_hi:[0,1,0]
	s_waitcnt lgkmcnt(4)
	s_cmp_eq_u32 s14, 0
	s_cbranch_scc1 .Lrw_skip_d0
	v_add_f32_dpp v48, v48, v48 row_ror:8 row_mask:0xf bank_mask:0x3
	v_add_f32_dpp v49, v49, v49 row_ror:8 row_mask:0xf bank_mask:0x3
	v_add_f32_dpp v50, v50, v50 row_ror:8 row_mask:0xf bank_mask:0x3
	v_add_f32_dpp v51, v51, v51 row_ror:8 row_mask:0xf bank_mask:0x3
	v_add_f32_dpp v52, v52, v52 row_ror:8 row_mask:0xf bank_mask:0x3
	v_add_f32_dpp v53, v53, v53 row_ror:8 row_mask:0xf bank_mask:0x3
	v_add_f32_dpp v54, v54, v54 row_ror:8 row_mask:0xf bank_mask:0x3
	v_add_f32_dpp v55, v55, v55 row_ror:8 row_mask:0xf bank_mask:0x3
	v_add_f32_dpp v48, v56, v56 row_ror:8 row_mask:0xf bank_mask:0xc
	v_add_f32_dpp v49, v57, v57 row_ror:8 row_mask:0xf bank_mask:0xc
	v_add_f32_dpp v50, v58, v58 row_ror:8 row_mask:0xf bank_mask:0xc
	v_add_f32_dpp v51, v59, v59 row_ror:8 row_mask:0xf bank_mask:0xc
	v_add_f32_dpp v52, v60, v60 row_ror:8 row_mask:0xf bank_mask:0xc
	v_add_f32_dpp v53, v61, v61 row_ror:8 row_mask:0xf bank_mask:0xc
	v_add_f32_dpp v54, v62, v62 row_ror:8 row_mask:0xf bank_mask:0xc
	v_add_f32_dpp v55, v63, v63 row_ror:8 row_mask:0xf bank_mask:0xc
	v_add_f32_dpp v48, v48, v48 row_ror:12 row_mask:0xf bank_mask:0x5
	v_add_f32_dpp v49, v49, v49 row_ror:12 row_mask:0xf bank_mask:0x5
	v_add_f32_dpp v50, v50, v50 row_ror:12 row_mask:0xf bank_mask:0x5
	v_add_f32_dpp v51, v51, v51 row_ror:12 row_mask:0xf bank_mask:0x5
	v_add_f32_dpp v48, v52, v52 row_ror:4 row_mask:0xf bank_mask:0xa
	v_add_f32_dpp v49, v53, v53 row_ror:4 row_mask:0xf bank_mask:0xa
	v_add_f32_dpp v50, v54, v54 row_ror:4 row_mask:0xf bank_mask:0xa
	v_add_f32_dpp v51, v55, v55 row_ror:4 row_mask:0xf bank_mask:0xa
	v_add_f32_dpp v64, v48, v48 quad_perm:[2,3,0,1] row_mask:0xf bank_mask:0xf bound_ctrl:1
	v_add_f32_dpp v65, v50, v50 quad_perm:[2,3,0,1] row_mask:0xf bank_mask:0xf bound_ctrl:1
	v_cndmask_b32_e64 v56, v64, v65, s[50:51]
	v_add_f32_dpp v64, v49, v49 quad_perm:[2,3,0,1] row_mask:0xf bank_mask:0xf bound_ctrl:1
	v_add_f32_dpp v65, v51, v51 quad_perm:[2,3,0,1] row_mask:0xf bank_mask:0xf bound_ctrl:1
	v_cndmask_b32_e64 v57, v64, v65, s[50:51]
	v_add_f32_dpp v64, v56, v56 quad_perm:[1,0,3,2] row_mask:0xf bank_mask:0xf bound_ctrl:1
	s_nop 0
	v_add_f32_dpp v65, v57, v57 quad_perm:[1,0,3,2] row_mask:0xf bank_mask:0xf bound_ctrl:1
	v_cndmask_b32_e64 v66, v64, v65, s[48:49]
	v_cvt_pk_bf16_f32 v66, v66, v66
	global_store_short v8, v66, s[12:13]
	s_add_u32 s12, s12, 0x8000
	s_addc_u32 s13, s13, 0
.Lrw_skip_d0:
	ds_read_b64 v[84:85], v6 offset:3088
	ds_read_b128 v[86:89], v6 offset:3344
	ds_read_b128 v[90:93], v6 offset:3600
	ds_read_u16 v94, v7 offset:3088
	v_fma_mix_f32 v14, v10, v38, 0 op_sel:[0,0,0] op_sel_hi:[0,1,0]
	v_fma_mix_f32 v48, v10, v32, 0 op_sel:[0,0,0] op_sel_hi:[0,1,0]
	v_fma_mix_f32 v14, v11, v38, v14 op_sel:[0,1,0] op_sel_hi:[0,1,0]
	v_fma_mix_f32 v48, v11, v32, v48 op_sel:[0,1,0] op_sel_hi:[0,1,0]
	v_fma_mix_f32 v14, v12, v39, v14 op_sel:[0,0,0] op_sel_hi:[0,1,0]
	v_fma_mix_f32 v48, v12, v33, v48 op_sel:[0,0,0] op_sel_hi:[0,1,0]
	v_fma_mix_f32 v14, v13, v39, v14 op_sel:[0,1,0] op_sel_hi:[0,1,0]
	v_fma_mix_f32 v16, v10, v36, 0 op_sel:[0,0,0] op_sel_hi:[0,1,0]
	v_fma_mix_f32 v17, v11, v36, 0 op_sel:[0,1,0] op_sel_hi:[0,1,0]
	v_add_f32_dpp v20, v14, v14 quad_perm:[1,0,3,2] row_mask:0xf bank_mask:0xf bound_ctrl:1
	v_fma_mix_f32 v48, v13, v33, v48 op_sel:[0,1,0] op_sel_hi:[0,1,0]
	v_fma_mix_f32 v18, v12, v37, 0 op_sel:[0,0,0] op_sel_hi:[0,1,0]
	v_add_f32_dpp v20, v20, v20 quad_perm:[2,3,0,1] row_mask:0xf bank_mask:0xf bound_ctrl:1
	v_fma_mix_f32 v19, v13, v37, 0 op_sel:[0,1,0] op_sel_hi:[0,1,0]
	v_fma_mix_f32 v16, v46, v42, v16 op_sel:[0,0,0] op_sel_hi:[1,1,0]
	v_add_f32_dpp v20, v20, v20 row_half_mirror row_mask:0xf bank_mask:0xf bound_ctrl:1
	v_fma_mix_f32 v17, v46, v42, v17 op_sel:[0,1,0] op_sel_hi:[1,1,0]
	v_fma_mix_f32 v18, v46, v43, v18 op_sel:[0,0,0] op_sel_hi:[1,1,0]
	v_add_f32_dpp v20, v20, v20 row_mirror row_mask:0xf bank_mask:0xf bound_ctrl:1
	v_fma_mix_f32 v19, v46, v43, v19 op_sel:[0,1,0] op_sel_hi:[1,1,0]
	v_fma_mix_f32 v10, v20, v40, v16 op_sel:[0,0,0] op_sel_hi:[0,1,0]
	v_fma_mix_f32 v11, v20, v40, v17 op_sel:[0,1,0] op_sel_hi:[0,1,0]
	v_fma_mix_f32 v12, v20, v41, v18 op_sel:[0,0,0] op_sel_hi:[0,1,0]
	v_fma_mix_f32 v13, v20, v41, v19 op_sel:[0,1,0] op_sel_hi:[0,1,0]
	s_waitcnt lgkmcnt(4)
	ds_read_b64 v[24:25], v6 offset:4112
	ds_read_b128 v[26:29], v6 offset:4368
	ds_read_b128 v[30:33], v6 offset:4624
	ds_read_u16 v34, v7 offset:4112
	v_fma_mix_f32 v14, v10, v74, 0 op_sel:[0,0,0] op_sel_hi:[0,1,0]
	v_fma_mix_f32 v49, v10, v44, 0 op_sel:[0,0,0] op_sel_hi:[0,1,0]
	v_fma_mix_f32 v14, v11, v74, v14 op_sel:[0,1,0] op_sel_hi:[0,1,0]
	v_fma_mix_f32 v49, v11, v44, v49 op_sel:[0,1,0] op_sel_hi:[0,1,0]
	v_fma_mix_f32 v14, v12, v75, v14 op_sel:[0,0,0] op_sel_hi:[0,1,0]
	v_fma_mix_f32 v49, v12, v45, v49 op_sel:[0,0,0] op_sel_hi:[0,1,0]
	v_fma_mix_f32 v14, v13, v75, v14 op_sel:[0,1,0] op_sel_hi:[0,1,0]
	v_fma_mix_f32 v16, v10, v72, 0 op_sel:[0,0,0] op_sel_hi:[0,1,0]
	v_fma_mix_f32 v17, v11, v72, 0 op_sel:[0,1,0] op_sel_hi:[0,1,0]
	v_add_f32_dpp v20, v14, v14 quad_perm:[1,0,3,2] row_mask:0xf bank_mask:0xf bound_ctrl:1
	v_fma_mix_f32 v49, v13, v45, v49 op_sel:[0,1,0] op_sel_hi:[0,1,0]
	v_fma_mix_f32 v18, v12, v73, 0 op_sel:[0,0,0] op_sel_hi:[0,1,0]
	v_add_f32_dpp v20, v20, v20 quad_perm:[2,3,0,1] row_mask:0xf bank_mask:0xf bound_ctrl:1
	v_fma_mix_f32 v19, v13, v73, 0 op_sel:[0,1,0] op_sel_hi:[0,1,0]
	v_fma_mix_f32 v16, v82, v78, v16 op_sel:[0,0,0] op_sel_hi:[1,1,0]
	v_add_f32_dpp v20, v20, v20 row_half_mirror row_mask:0xf bank_mask:0xf bound_ctrl:1
	v_fma_mix_f32 v17, v82, v78, v17 op_sel:[0,1,0] op_sel_hi:[1,1,0]
	v_fma_mix_f32 v18, v82, v79, v18 op_sel:[0,0,0] op_sel_hi:[1,1,0]
	v_add_f32_dpp v20, v20, v20 row_mirror row_mask:0xf bank_mask:0xf bound_ctrl:1
	v_fma_mix_f32 v19, v82, v79, v19 op_sel:[0,1,0] op_sel_hi:[1,1,0]
	v_fma_mix_f32 v10, v20, v76, v16 op_sel:[0,0,0] op_sel_hi:[0,1,0]
	v_fma_mix_f32 v11, v20, v76, v17 op_sel:[0,1,0] op_sel_hi:[0,1,0]
	v_fma_mix_f32 v12, v20, v77, v18 op_sel:[0,0,0] op_sel_hi:[0,1,0]
	v_fma_mix_f32 v13, v20, v77, v19 op_sel:[0,1,0] op_sel_hi:[0,1,0]
	s_waitcnt lgkmcnt(4)
	ds_read_b64 v[36:37], v6 offset:5136
	ds_read_b128 v[38:41], v6 offset:5392
	ds_read_b128 v[42:45], v6 offset:5648
	ds_read_u16 v46, v7 offset:5136
	v_fma_mix_f32 v14, v10, v86, 0 op_sel:[0,0,0] op_sel_hi:[0,1,0]
	v_fma_mix_f32 v50, v10, v80, 0 op_sel:[0,0,0] op_sel_hi:[0,1,0]
	v_fma_mix_f32 v14, v11, v86, v14 op_sel:[0,1,0] op_sel_hi:[0,1,0]
	v_fma_mix_f32 v50, v11, v80, v50 op_sel:[0,1,0] op_sel_hi:[0,1,0]
	v_fma_mix_f32 v14, v12, v87, v14 op_sel:[0,0,0] op_sel_hi:[0,1,0]
	v_fma_mix_f32 v50, v12, v81, v50 op_sel:[0,0,0] op_sel_hi:[0,1,0]
	v_fma_mix_f32 v14, v13, v87, v14 op_sel:[0,1,0] op_sel_hi:[0,1,0]
	v_fma_mix_f32 v16, v10, v84, 0 op_sel:[0,0,0] op_sel_hi:[0,1,0]
	v_fma_mix_f32 v17, v11, v84, 0 op_sel:[0,1,0] op_sel_hi:[0,1,0]
	v_add_f32_dpp v20, v14, v14 quad_perm:[1,0,3,2] row_mask:0xf bank_mask:0xf bound_ctrl:1
	v_fma_mix_f32 v50, v13, v81, v50 op_sel:[0,1,0] op_sel_hi:[0,1,0]
	v_fma_mix_f32 v18, v12, v85, 0 op_sel:[0,0,0] op_sel_hi:[0,1,0]
	v_add_f32_dpp v20, v20, v20 quad_perm:[2,3,0,1] row_mask:0xf bank_mask:0xf bound_ctrl:1
	v_fma_mix_f32 v19, v13, v85, 0 op_sel:[0,1,0] op_sel_hi:[0,1,0]
	v_fma_mix_f32 v16, v94, v90, v16 op_sel:[0,0,0] op_sel_hi:[1,1,0]
	v_add_f32_dpp v20, v20, v20 row_half_mirror row_mask:0xf bank_mask:0xf bound_ctrl:1
	v_fma_mix_f32 v17, v94, v90, v17 op_sel:[0,1,0] op_sel_hi:[1,1,0]
	v_fma_mix_f32 v18, v94, v91, v18 op_sel:[0,0,0] op_sel_hi:[1,1,0]
	v_add_f32_dpp v20, v20, v20 row_mirror row_mask:0xf bank_mask:0xf bound_ctrl:1
	v_fma_mix_f32 v19, v94, v91, v19 op_sel:[0,1,0] op_sel_hi:[1,1,0]
	v_fma_mix_f32 v10, v20, v88, v16 op_sel:[0,0,0] op_sel_hi:[0,1,0]
	v_fma_mix_f32 v11, v20, v88, v17 op_sel:[0,1,0] op_sel_hi:[0,1,0]
	v_fma_mix_f32 v12, v20, v89, v18 op_sel:[0,0,0] op_sel_hi:[0,1,0]
	v_fma_mix_f32 v13, v20, v89, v19 op_sel:[0,1,0] op_sel_hi:[0,1,0]
	s_waitcnt lgkmcnt(4)
	ds_read_b64 v[72:73], v6 offset:6160
	ds_read_b128 v[74:77], v6 offset:6416
	ds_read_b128 v[78:81], v6 offset:6672
	ds_read_u16 v82, v7 offset:6160
	v_fma_mix_f32 v14, v10, v26, 0 op_sel:[0,0,0] op_sel_hi:[0,1,0]
	v_fma_mix_f32 v51, v10, v92, 0 op_sel:[0,0,0] op_sel_hi:[0,1,0]
	v_fma_mix_f32 v14, v11, v26, v14 op_sel:[0,1,0] op_sel_hi:[0,1,0]
	v_fma_mix_f32 v51, v11, v92, v51 op_sel:[0,1,0] op_sel_hi:[0,1,0]
	v_fma_mix_f32 v14, v12, v27, v14 op_sel:[0,0,0] op_sel_hi:[0,1,0]
	v_fma_mix_f32 v51, v12, v93, v51 op_sel:[0,0,0] op_sel_hi:[0,1,0]
	v_fma_mix_f32 v14, v13, v27, v14 op_sel:[0,1,0] op_sel_hi:[0,1,0]
	v_fma_mix_f32 v16, v10, v24, 0 op_sel:[0,0,0] op_sel_hi:[0,1,0]
	v_fma_mix_f32 v17, v11, v24, 0 op_sel:[0,1,0] op_sel_hi:[0,1,0]
	v_add_f32_dpp v20, v14, v14 quad_perm:[1,0,3,2] row_mask:0xf bank_mask:0xf bound_ctrl:1
	v_fma_mix_f32 v51, v13, v93, v51 op_sel:[0,1,0] op_sel_hi:[0,1,0]
	v_fma_mix_f32 v18, v12, v25, 0 op_sel:[0,0,0] op_sel_hi:[0,1,0]
	v_add_f32_dpp v20, v20, v20 quad_perm:[2,3,0,1] row_mask:0xf bank_mask:0xf bound_ctrl:1
	v_fma_mix_f32 v19, v13, v25, 0 op_sel:[0,1,0] op_sel_hi:[0,1,0]
	v_fma_mix_f32 v16, v34, v30, v16 op_sel:[0,0,0] op_sel_hi:[1,1,0]
	v_add_f32_dpp v20, v20, v20 row_half_mirror row_mask:0xf bank_mask:0xf bound_ctrl:1
	v_fma_mix_f32 v17, v34, v30, v17 op_sel:[0,1,0] op_sel_hi:[1,1,0]
	v_fma_mix_f32 v18, v34, v31, v18 op_sel:[0,0,0] op_sel_hi:[1,1,0]
	v_add_f32_dpp v20, v20, v20 row_mirror row_mask:0xf bank_mask:0xf bound_ctrl:1
	v_fma_mix_f32 v19, v34, v31, v19 op_sel:[0,1,0] op_sel_hi:[1,1,0]
	v_fma_mix_f32 v10, v20, v28, v16 op_sel:[0,0,0] op_sel_hi:[0,1,0]
	v_fma_mix_f32 v11, v20, v28, v17 op_sel:[0,1,0] op_sel_hi:[0,1,0]
	v_fma_mix_f32 v12, v20, v29, v18 op_sel:[0,0,0] op_sel_hi:[0,1,0]
	v_fma_mix_f32 v13, v20, v29, v19 op_sel:[0,1,0] op_sel_hi:[0,1,0]
	s_waitcnt lgkmcnt(4)
	ds_read_b64 v[84:85], v6 offset:7184
	ds_read_b128 v[86:89], v6 offset:7440
	ds_read_b128 v[90:93], v6 offset:7696
	ds_read_u16 v94, v7 offset:7184
	v_fma_mix_f32 v14, v10, v38, 0 op_sel:[0,0,0] op_sel_hi:[0,1,0]
	v_fma_mix_f32 v52, v10, v32, 0 op_sel:[0,0,0] op_sel_hi:[0,1,0]
	v_fma_mix_f32 v14, v11, v38, v14 op_sel:[0,1,0] op_sel_hi:[0,1,0]
	v_fma_mix_f32 v52, v11, v32, v52 op_sel:[0,1,0] op_sel_hi:[0,1,0]
	v_fma_mix_f32 v14, v12, v39, v14 op_sel:[0,0,0] op_sel_hi:[0,1,0]
	v_fma_mix_f32 v52, v12, v33, v52 op_sel:[0,0,0] op_sel_hi:[0,1,0]
	v_fma_mix_f32 v14, v13, v39, v14 op_sel:[0,1,0] op_sel_hi:[0,1,0]
	v_fma_mix_f32 v16, v10, v36, 0 op_sel:[0,0,0] op_sel_hi:[0,1,0]
	v_fma_mix_f32 v17, v11, v36, 0 op_sel:[0,1,0] op_sel_hi:[0,1,0]
	v_add_f32_dpp v20, v14, v14 quad_perm:[1,0,3,2] row_mask:0xf bank_mask:0xf bound_ctrl:1
	v_fma_mix_f32 v52, v13, v33, v52 op_sel:[0,1,0] op_sel_hi:[0,1,0]
	v_fma_mix_f32 v18, v12, v37, 0 op_sel:[0,0,0] op_sel_hi:[0,1,0]
	v_add_f32_dpp v20, v20, v20 quad_perm:[2,3,0,1] row_mask:0xf bank_mask:0xf bound_ctrl:1
	v_fma_mix_f32 v19, v13, v37, 0 op_sel:[0,1,0] op_sel_hi:[0,1,0]
	v_fma_mix_f32 v16, v46, v42, v16 op_sel:[0,0,0] op_sel_hi:[1,1,0]
	v_add_f32_dpp v20, v20, v20 row_half_mirror row_mask:0xf bank_mask:0xf bound_ctrl:1
	v_fma_mix_f32 v17, v46, v42, v17 op_sel:[0,1,0] op_sel_hi:[1,1,0]
	v_fma_mix_f32 v18, v46, v43, v18 op_sel:[0,0,0] op_sel_hi:[1,1,0]
	v_add_f32_dpp v20, v20, v20 row_mirror row_mask:0xf bank_mask:0xf bound_ctrl:1
	v_fma_mix_f32 v19, v46, v43, v19 op_sel:[0,1,0] op_sel_hi:[1,1,0]
	v_fma_mix_f32 v10, v20, v40, v16 op_sel:[0,0,0] op_sel_hi:[0,1,0]
	v_fma_mix_f32 v11, v20, v40, v17 op_sel:[0,1,0] op_sel_hi:[0,1,0]
	v_fma_mix_f32 v12, v20, v41, v18 op_sel:[0,0,0] op_sel_hi:[0,1,0]
	v_fma_mix_f32 v13, v20, v41, v19 op_sel:[0,1,0] op_sel_hi:[0,1,0]
	s_waitcnt lgkmcnt(4)
	ds_read_b64 v[24:25], v6 offset:8208
	ds_read_b128 v[26:29], v6 offset:8464
	ds_read_b128 v[30:33], v6 offset:8720
	ds_read_u16 v34, v7 offset:8208
	v_fma_mix_f32 v14, v10, v74, 0 op_sel:[0,0,0] op_sel_hi:[0,1,0]
	v_fma_mix_f32 v53, v10, v44, 0 op_sel:[0,0,0] op_sel_hi:[0,1,0]
	v_fma_mix_f32 v14, v11, v74, v14 op_sel:[0,1,0] op_sel_hi:[0,1,0]
	v_fma_mix_f32 v53, v11, v44, v53 op_sel:[0,1,0] op_sel_hi:[0,1,0]
	v_fma_mix_f32 v14, v12, v75, v14 op_sel:[0,0,0] op_sel_hi:[0,1,0]
	v_fma_mix_f32 v53, v12, v45, v53 op_sel:[0,0,0] op_sel_hi:[0,1,0]
	v_fma_mix_f32 v14, v13, v75, v14 op_sel:[0,1,0] op_sel_hi:[0,1,0]
	v_fma_mix_f32 v16, v10, v72, 0 op_sel:[0,0,0] op_sel_hi:[0,1,0]
	v_fma_mix_f32 v17, v11, v72, 0 op_sel:[0,1,0] op_sel_hi:[0,1,0]
	v_add_f32_dpp v20, v14, v14 quad_perm:[1,0,3,2] row_mask:0xf bank_mask:0xf bound_ctrl:1
	v_fma_mix_f32 v53, v13, v45, v53 op_sel:[0,1,0] op_sel_hi:[0,1,0]
	v_fma_mix_f32 v18, v12, v73, 0 op_sel:[0,0,0] op_sel_hi:[0,1,0]
	v_add_f32_dpp v20, v20, v20 quad_perm:[2,3,0,1] row_mask:0xf bank_mask:0xf bound_ctrl:1
	v_fma_mix_f32 v19, v13, v73, 0 op_sel:[0,1,0] op_sel_hi:[0,1,0]
	v_fma_mix_f32 v16, v82, v78, v16 op_sel:[0,0,0] op_sel_hi:[1,1,0]
	v_add_f32_dpp v20, v20, v20 row_half_mirror row_mask:0xf bank_mask:0xf bound_ctrl:1
	v_fma_mix_f32 v17, v82, v78, v17 op_sel:[0,1,0] op_sel_hi:[1,1,0]
	v_fma_mix_f32 v18, v82, v79, v18 op_sel:[0,0,0] op_sel_hi:[1,1,0]
	v_add_f32_dpp v20, v20, v20 row_mirror row_mask:0xf bank_mask:0xf bound_ctrl:1
	v_fma_mix_f32 v19, v82, v79, v19 op_sel:[0,1,0] op_sel_hi:[1,1,0]
	v_fma_mix_f32 v10, v20, v76, v16 op_sel:[0,0,0] op_sel_hi:[0,1,0]
	v_fma_mix_f32 v11, v20, v76, v17 op_sel:[0,1,0] op_sel_hi:[0,1,0]
	v_fma_mix_f32 v12, v20, v77, v18 op_sel:[0,0,0] op_sel_hi:[0,1,0]
	v_fma_mix_f32 v13, v20, v77, v19 op_sel:[0,1,0] op_sel_hi:[0,1,0]
	s_waitcnt lgkmcnt(4)
	ds_read_b64 v[36:37], v6 offset:9232
	ds_read_b128 v[38:41], v6 offset:9488
	ds_read_b128 v[42:45], v6 offset:9744
	ds_read_u16 v46, v7 offset:9232
	v_fma_mix_f32 v14, v10, v86, 0 op_sel:[0,0,0] op_sel_hi:[0,1,0]
	v_fma_mix_f32 v54, v10, v80, 0 op_sel:[0,0,0] op_sel_hi:[0,1,0]
	v_fma_mix_f32 v14, v11, v86, v14 op_sel:[0,1,0] op_sel_hi:[0,1,0]
	v_fma_mix_f32 v54, v11, v80, v54 op_sel:[0,1,0] op_sel_hi:[0,1,0]
	v_fma_mix_f32 v14, v12, v87, v14 op_sel:[0,0,0] op_sel_hi:[0,1,0]
	v_fma_mix_f32 v54, v12, v81, v54 op_sel:[0,0,0] op_sel_hi:[0,1,0]
	v_fma_mix_f32 v14, v13, v87, v14 op_sel:[0,1,0] op_sel_hi:[0,1,0]
	v_fma_mix_f32 v16, v10, v84, 0 op_sel:[0,0,0] op_sel_hi:[0,1,0]
	v_fma_mix_f32 v17, v11, v84, 0 op_sel:[0,1,0] op_sel_hi:[0,1,0]
	v_add_f32_dpp v20, v14, v14 quad_perm:[1,0,3,2] row_mask:0xf bank_mask:0xf bound_ctrl:1
	v_fma_mix_f32 v54, v13, v81, v54 op_sel:[0,1,0] op_sel_hi:[0,1,0]
	v_fma_mix_f32 v18, v12, v85, 0 op_sel:[0,0,0] op_sel_hi:[0,1,0]
	v_add_f32_dpp v20, v20, v20 quad_perm:[2,3,0,1] row_mask:0xf bank_mask:0xf bound_ctrl:1
	v_fma_mix_f32 v19, v13, v85, 0 op_sel:[0,1,0] op_sel_hi:[0,1,0]
	v_fma_mix_f32 v16, v94, v90, v16 op_sel:[0,0,0] op_sel_hi:[1,1,0]
	v_add_f32_dpp v20, v20, v20 row_half_mirror row_mask:0xf bank_mask:0xf bound_ctrl:1
	v_fma_mix_f32 v17, v94, v90, v17 op_sel:[0,1,0] op_sel_hi:[1,1,0]
	v_fma_mix_f32 v18, v94, v91, v18 op_sel:[0,0,0] op_sel_hi:[1,1,0]
	v_add_f32_dpp v20, v20, v20 row_mirror row_mask:0xf bank_mask:0xf bound_ctrl:1
	v_fma_mix_f32 v19, v94, v91, v19 op_sel:[0,1,0] op_sel_hi:[1,1,0]
	v_fma_mix_f32 v10, v20, v88, v16 op_sel:[0,0,0] op_sel_hi:[0,1,0]
	v_fma_mix_f32 v11, v20, v88, v17 op_sel:[0,1,0] op_sel_hi:[0,1,0]
	v_fma_mix_f32 v12, v20, v89, v18 op_sel:[0,0,0] op_sel_hi:[0,1,0]
	v_fma_mix_f32 v13, v20, v89, v19 op_sel:[0,1,0] op_sel_hi:[0,1,0]
	s_waitcnt lgkmcnt(4)
	ds_read_b64 v[72:73], v6 offset:10256
	ds_read_b128 v[74:77], v6 offset:10512
	ds_read_b128 v[78:81], v6 offset:10768
	ds_read_u16 v82, v7 offset:10256
	v_fma_mix_f32 v14, v10, v26, 0 op_sel:[0,0,0] op_sel_hi:[0,1,0]
	v_fma_mix_f32 v55, v10, v92, 0 op_sel:[0,0,0] op_sel_hi:[0,1,0]
	v_fma_mix_f32 v14, v11, v26, v14 op_sel:[0,1,0] op_sel_hi:[0,1,0]
	v_fma_mix_f32 v55, v11, v92, v55 op_sel:[0,1,0] op_sel_hi:[0,1,0]
	v_fma_mix_f32 v14, v12, v27, v14 op_sel:[0,0,0] op_sel_hi:[0,1,0]
	v_fma_mix_f32 v55, v12, v93, v55 op_sel:[0,0,0] op_sel_hi:[0,1,0]
	v_fma_mix_f32 v14, v13, v27, v14 op_sel:[0,1,0] op_sel_hi:[0,1,0]
	v_fma_mix_f32 v16, v10, v24, 0 op_sel:[0,0,0] op_sel_hi:[0,1,0]
	v_fma_mix_f32 v17, v11, v24, 0 op_sel:[0,1,0] op_sel_hi:[0,1,0]
	v_add_f32_dpp v20, v14, v14 quad_perm:[1,0,3,2] row_mask:0xf bank_mask:0xf bound_ctrl:1
	v_fma_mix_f32 v55, v13, v93, v55 op_sel:[0,1,0] op_sel_hi:[0,1,0]
	v_fma_mix_f32 v18, v12, v25, 0 op_sel:[0,0,0] op_sel_hi:[0,1,0]
	v_add_f32_dpp v20, v20, v20 quad_perm:[2,3,0,1] row_mask:0xf bank_mask:0xf bound_ctrl:1
	v_fma_mix_f32 v19, v13, v25, 0 op_sel:[0,1,0] op_sel_hi:[0,1,0]
	v_fma_mix_f32 v16, v34, v30, v16 op_sel:[0,0,0] op_sel_hi:[1,1,0]
	v_add_f32_dpp v20, v20, v20 row_half_mirror row_mask:0xf bank_mask:0xf bound_ctrl:1
	v_fma_mix_f32 v17, v34, v30, v17 op_sel:[0,1,0] op_sel_hi:[1,1,0]
	v_fma_mix_f32 v18, v34, v31, v18 op_sel:[0,0,0] op_sel_hi:[1,1,0]
	v_add_f32_dpp v20, v20, v20 row_mirror row_mask:0xf bank_mask:0xf bound_ctrl:1
	v_fma_mix_f32 v19, v34, v31, v19 op_sel:[0,1,0] op_sel_hi:[1,1,0]
	v_fma_mix_f32 v10, v20, v28, v16 op_sel:[0,0,0] op_sel_hi:[0,1,0]
	v_fma_mix_f32 v11, v20, v28, v17 op_sel:[0,1,0] op_sel_hi:[0,1,0]
	v_fma_mix_f32 v12, v20, v29, v18 op_sel:[0,0,0] op_sel_hi:[0,1,0]
	v_fma_mix_f32 v13, v20, v29, v19 op_sel:[0,1,0] op_sel_hi:[0,1,0]
	s_waitcnt lgkmcnt(4)
	ds_read_b64 v[84:85], v6 offset:11280
	ds_read_b128 v[86:89], v6 offset:11536
	ds_read_b128 v[90:93], v6 offset:11792
	ds_read_u16 v94, v7 offset:11280
	v_fma_mix_f32 v14, v10, v38, 0 op_sel:[0,0,0] op_sel_hi:[0,1,0]
	v_fma_mix_f32 v56, v10, v32, 0 op_sel:[0,0,0] op_sel_hi:[0,1,0]
	v_fma_mix_f32 v14, v11, v38, v14 op_sel:[0,1,0] op_sel_hi:[0,1,0]
	v_fma_mix_f32 v56, v11, v32, v56 op_sel:[0,1,0] op_sel_hi:[0,1,0]
	v_fma_mix_f32 v14, v12, v39, v14 op_sel:[0,0,0] op_sel_hi:[0,1,0]
	v_fma_mix_f32 v56, v12, v33, v56 op_sel:[0,0,0] op_sel_hi:[0,1,0]
	v_fma_mix_f32 v14, v13, v39, v14 op_sel:[0,1,0] op_sel_hi:[0,1,0]
	v_fma_mix_f32 v16, v10, v36, 0 op_sel:[0,0,0] op_sel_hi:[0,1,0]
	v_fma_mix_f32 v17, v11, v36, 0 op_sel:[0,1,0] op_sel_hi:[0,1,0]
	v_add_f32_dpp v20, v14, v14 quad_perm:[1,0,3,2] row_mask:0xf bank_mask:0xf bound_ctrl:1
	v_fma_mix_f32 v56, v13, v33, v56 op_sel:[0,1,0] op_sel_hi:[0,1,0]
	v_fma_mix_f32 v18, v12, v37, 0 op_sel:[0,0,0] op_sel_hi:[0,1,0]
	v_add_f32_dpp v20, v20, v20 quad_perm:[2,3,0,1] row_mask:0xf bank_mask:0xf bound_ctrl:1
	v_fma_mix_f32 v19, v13, v37, 0 op_sel:[0,1,0] op_sel_hi:[0,1,0]
	v_fma_mix_f32 v16, v46, v42, v16 op_sel:[0,0,0] op_sel_hi:[1,1,0]
	v_add_f32_dpp v20, v20, v20 row_half_mirror row_mask:0xf bank_mask:0xf bound_ctrl:1
	v_fma_mix_f32 v17, v46, v42, v17 op_sel:[0,1,0] op_sel_hi:[1,1,0]
	v_fma_mix_f32 v18, v46, v43, v18 op_sel:[0,0,0] op_sel_hi:[1,1,0]
	v_add_f32_dpp v20, v20, v20 row_mirror row_mask:0xf bank_mask:0xf bound_ctrl:1
	v_fma_mix_f32 v19, v46, v43, v19 op_sel:[0,1,0] op_sel_hi:[1,1,0]
	v_fma_mix_f32 v10, v20, v40, v16 op_sel:[0,0,0] op_sel_hi:[0,1,0]
	v_fma_mix_f32 v11, v20, v40, v17 op_sel:[0,1,0] op_sel_hi:[0,1,0]
	v_fma_mix_f32 v12, v20, v41, v18 op_sel:[0,0,0] op_sel_hi:[0,1,0]
	v_fma_mix_f32 v13, v20, v41, v19 op_sel:[0,1,0] op_sel_hi:[0,1,0]
	s_waitcnt lgkmcnt(4)
	ds_read_b64 v[24:25], v6 offset:12304
	ds_read_b128 v[26:29], v6 offset:12560
	ds_read_b128 v[30:33], v6 offset:12816
	ds_read_u16 v34, v7 offset:12304
	v_fma_mix_f32 v14, v10, v74, 0 op_sel:[0,0,0] op_sel_hi:[0,1,0]
	v_fma_mix_f32 v57, v10, v44, 0 op_sel:[0,0,0] op_sel_hi:[0,1,0]
	v_fma_mix_f32 v14, v11, v74, v14 op_sel:[0,1,0] op_sel_hi:[0,1,0]
	v_fma_mix_f32 v57, v11, v44, v57 op_sel:[0,1,0] op_sel_hi:[0,1,0]
	v_fma_mix_f32 v14, v12, v75, v14 op_sel:[0,0,0] op_sel_hi:[0,1,0]
	v_fma_mix_f32 v57, v12, v45, v57 op_sel:[0,0,0] op_sel_hi:[0,1,0]
	v_fma_mix_f32 v14, v13, v75, v14 op_sel:[0,1,0] op_sel_hi:[0,1,0]
	v_fma_mix_f32 v16, v10, v72, 0 op_sel:[0,0,0] op_sel_hi:[0,1,0]
	v_fma_mix_f32 v17, v11, v72, 0 op_sel:[0,1,0] op_sel_hi:[0,1,0]
	v_add_f32_dpp v20, v14, v14 quad_perm:[1,0,3,2] row_mask:0xf bank_mask:0xf bound_ctrl:1
	v_fma_mix_f32 v57, v13, v45, v57 op_sel:[0,1,0] op_sel_hi:[0,1,0]
	v_fma_mix_f32 v18, v12, v73, 0 op_sel:[0,0,0] op_sel_hi:[0,1,0]
	v_add_f32_dpp v20, v20, v20 quad_perm:[2,3,0,1] row_mask:0xf bank_mask:0xf bound_ctrl:1
	v_fma_mix_f32 v19, v13, v73, 0 op_sel:[0,1,0] op_sel_hi:[0,1,0]
	v_fma_mix_f32 v16, v82, v78, v16 op_sel:[0,0,0] op_sel_hi:[1,1,0]
	v_add_f32_dpp v20, v20, v20 row_half_mirror row_mask:0xf bank_mask:0xf bound_ctrl:1
	v_fma_mix_f32 v17, v82, v78, v17 op_sel:[0,1,0] op_sel_hi:[1,1,0]
	v_fma_mix_f32 v18, v82, v79, v18 op_sel:[0,0,0] op_sel_hi:[1,1,0]
	v_add_f32_dpp v20, v20, v20 row_mirror row_mask:0xf bank_mask:0xf bound_ctrl:1
	v_fma_mix_f32 v19, v82, v79, v19 op_sel:[0,1,0] op_sel_hi:[1,1,0]
	v_fma_mix_f32 v10, v20, v76, v16 op_sel:[0,0,0] op_sel_hi:[0,1,0]
	v_fma_mix_f32 v11, v20, v76, v17 op_sel:[0,1,0] op_sel_hi:[0,1,0]
	v_fma_mix_f32 v12, v20, v77, v18 op_sel:[0,0,0] op_sel_hi:[0,1,0]
	v_fma_mix_f32 v13, v20, v77, v19 op_sel:[0,1,0] op_sel_hi:[0,1,0]
	s_waitcnt lgkmcnt(4)
	ds_read_b64 v[36:37], v6 offset:13328
	ds_read_b128 v[38:41], v6 offset:13584
	ds_read_b128 v[42:45], v6 offset:13840
	ds_read_u16 v46, v7 offset:13328
	v_fma_mix_f32 v14, v10, v86, 0 op_sel:[0,0,0] op_sel_hi:[0,1,0]
	v_fma_mix_f32 v58, v10, v80, 0 op_sel:[0,0,0] op_sel_hi:[0,1,0]
	v_fma_mix_f32 v14, v11, v86, v14 op_sel:[0,1,0] op_sel_hi:[0,1,0]
	v_fma_mix_f32 v58, v11, v80, v58 op_sel:[0,1,0] op_sel_hi:[0,1,0]
	v_fma_mix_f32 v14, v12, v87, v14 op_sel:[0,0,0] op_sel_hi:[0,1,0]
	v_fma_mix_f32 v58, v12, v81, v58 op_sel:[0,0,0] op_sel_hi:[0,1,0]
	v_fma_mix_f32 v14, v13, v87, v14 op_sel:[0,1,0] op_sel_hi:[0,1,0]
	v_fma_mix_f32 v16, v10, v84, 0 op_sel:[0,0,0] op_sel_hi:[0,1,0]
	v_fma_mix_f32 v17, v11, v84, 0 op_sel:[0,1,0] op_sel_hi:[0,1,0]
	v_add_f32_dpp v20, v14, v14 quad_perm:[1,0,3,2] row_mask:0xf bank_mask:0xf bound_ctrl:1
	v_fma_mix_f32 v58, v13, v81, v58 op_sel:[0,1,0] op_sel_hi:[0,1,0]
	v_fma_mix_f32 v18, v12, v85, 0 op_sel:[0,0,0] op_sel_hi:[0,1,0]
	v_add_f32_dpp v20, v20, v20 quad_perm:[2,3,0,1] row_mask:0xf bank_mask:0xf bound_ctrl:1
	v_fma_mix_f32 v19, v13, v85, 0 op_sel:[0,1,0] op_sel_hi:[0,1,0]
	v_fma_mix_f32 v16, v94, v90, v16 op_sel:[0,0,0] op_sel_hi:[1,1,0]
	v_add_f32_dpp v20, v20, v20 row_half_mirror row_mask:0xf bank_mask:0xf bound_ctrl:1
	v_fma_mix_f32 v17, v94, v90, v17 op_sel:[0,1,0] op_sel_hi:[1,1,0]
	v_fma_mix_f32 v18, v94, v91, v18 op_sel:[0,0,0] op_sel_hi:[1,1,0]
	v_add_f32_dpp v20, v20, v20 row_mirror row_mask:0xf bank_mask:0xf bound_ctrl:1
	v_fma_mix_f32 v19, v94, v91, v19 op_sel:[0,1,0] op_sel_hi:[1,1,0]
	v_fma_mix_f32 v10, v20, v88, v16 op_sel:[0,0,0] op_sel_hi:[0,1,0]
	v_fma_mix_f32 v11, v20, v88, v17 op_sel:[0,1,0] op_sel_hi:[0,1,0]
	v_fma_mix_f32 v12, v20, v89, v18 op_sel:[0,0,0] op_sel_hi:[0,1,0]
	v_fma_mix_f32 v13, v20, v89, v19 op_sel:[0,1,0] op_sel_hi:[0,1,0]
	s_waitcnt lgkmcnt(4)
	ds_read_b64 v[72:73], v6 offset:14352
	ds_read_b128 v[74:77], v6 offset:14608
	ds_read_b128 v[78:81], v6 offset:14864
	ds_read_u16 v82, v7 offset:14352
	v_fma_mix_f32 v14, v10, v26, 0 op_sel:[0,0,0] op_sel_hi:[0,1,0]
	v_fma_mix_f32 v59, v10, v92, 0 op_sel:[0,0,0] op_sel_hi:[0,1,0]
	v_fma_mix_f32 v14, v11, v26, v14 op_sel:[0,1,0] op_sel_hi:[0,1,0]
	v_fma_mix_f32 v59, v11, v92, v59 op_sel:[0,1,0] op_sel_hi:[0,1,0]
	v_fma_mix_f32 v14, v12, v27, v14 op_sel:[0,0,0] op_sel_hi:[0,1,0]
	v_fma_mix_f32 v59, v12, v93, v59 op_sel:[0,0,0] op_sel_hi:[0,1,0]
	v_fma_mix_f32 v14, v13, v27, v14 op_sel:[0,1,0] op_sel_hi:[0,1,0]
	v_fma_mix_f32 v16, v10, v24, 0 op_sel:[0,0,0] op_sel_hi:[0,1,0]
	v_fma_mix_f32 v17, v11, v24, 0 op_sel:[0,1,0] op_sel_hi:[0,1,0]
	v_add_f32_dpp v20, v14, v14 quad_perm:[1,0,3,2] row_mask:0xf bank_mask:0xf bound_ctrl:1
	v_fma_mix_f32 v59, v13, v93, v59 op_sel:[0,1,0] op_sel_hi:[0,1,0]
	v_fma_mix_f32 v18, v12, v25, 0 op_sel:[0,0,0] op_sel_hi:[0,1,0]
	v_add_f32_dpp v20, v20, v20 quad_perm:[2,3,0,1] row_mask:0xf bank_mask:0xf bound_ctrl:1
	v_fma_mix_f32 v19, v13, v25, 0 op_sel:[0,1,0] op_sel_hi:[0,1,0]
	v_fma_mix_f32 v16, v34, v30, v16 op_sel:[0,0,0] op_sel_hi:[1,1,0]
	v_add_f32_dpp v20, v20, v20 row_half_mirror row_mask:0xf bank_mask:0xf bound_ctrl:1
	v_fma_mix_f32 v17, v34, v30, v17 op_sel:[0,1,0] op_sel_hi:[1,1,0]
	v_fma_mix_f32 v18, v34, v31, v18 op_sel:[0,0,0] op_sel_hi:[1,1,0]
	v_add_f32_dpp v20, v20, v20 row_mirror row_mask:0xf bank_mask:0xf bound_ctrl:1
	v_fma_mix_f32 v19, v34, v31, v19 op_sel:[0,1,0] op_sel_hi:[1,1,0]
	v_fma_mix_f32 v10, v20, v28, v16 op_sel:[0,0,0] op_sel_hi:[0,1,0]
	v_fma_mix_f32 v11, v20, v28, v17 op_sel:[0,1,0] op_sel_hi:[0,1,0]
	v_fma_mix_f32 v12, v20, v29, v18 op_sel:[0,0,0] op_sel_hi:[0,1,0]
	v_fma_mix_f32 v13, v20, v29, v19 op_sel:[0,1,0] op_sel_hi:[0,1,0]
	s_waitcnt lgkmcnt(4)
; DEVINL u16 f2bf(float a) { return (u16)(pk2(a, 0.f) & 0xffffu); }
; #define RW_STEP2(B) RW_STEP(B, WvA, XA, KrA, vhA, WvB, XB, KrB, vhB); RW_STEP((B) + 1, WvB, XB, KrB, vhB, WvA, XA, KrA, vhA)
; #define RW_STEP4(B) RW_STEP2(B); RW_STEP2((B) + 2)
; template <int DIR>
; DEVINL void rwkv_scan_dir(const Params& p, int task, int lane, int wave) {
;     ...
; #pragma unroll 1
;   for (int st = 0; st < 4096; st += 32) {
;     RW_STEP(0, WvA, XA, KrA, vhA, WvB, XB, KrB, vhB);
;     if (st > 0) { const int q0 = st - 16 + seg; yo[(long)(DIR ? (4095 - q0) : q0) * 1024] = f2bf(ykeep); }
;     RW_STEP(1, WvB, XB, KrB, vhB, WvA, XA, KrA, vhA);
;     RW_STEP2(2); RW_STEP4(4); RW_STEP4(8); RW_STEP4(12);
;     RW_STEP(16, WvA, XA, KrA, vhA, WvB, XB, KrB, vhB);
;     { const int q0 = st + seg; yo[(long)(DIR ? (4095 - q0) : q0) * 1024] = f2bf(ykeep); }
;     RW_STEP(17, WvB, XB, KrB, vhB, WvA, XA, KrA, vhA);
;     RW_STEP2(18); RW_STEP4(20); RW_STEP4(24); RW_STEP4(28);
;   }
	ds_read_b64 v[84:85], v6 offset:15376
	ds_read_b128 v[86:89], v6 offset:15632
	ds_read_b128 v[90:93], v6 offset:15888
	ds_read_u16 v94, v7 offset:15376
	v_fma_mix_f32 v14, v10, v38, 0 op_sel:[0,0,0] op_sel_hi:[0,1,0]
	v_fma_mix_f32 v60, v10, v32, 0 op_sel:[0,0,0] op_sel_hi:[0,1,0]
	v_fma_mix_f32 v14, v11, v38, v14 op_sel:[0,1,0] op_sel_hi:[0,1,0]
	v_fma_mix_f32 v60, v11, v32, v60 op_sel:[0,1,0] op_sel_hi:[0,1,0]
	v_fma_mix_f32 v14, v12, v39, v14 op_sel:[0,0,0] op_sel_hi:[0,1,0]
	v_fma_mix_f32 v60, v12, v33, v60 op_sel:[0,0,0] op_sel_hi:[0,1,0]
	v_fma_mix_f32 v14, v13, v39, v14 op_sel:[0,1,0] op_sel_hi:[0,1,0]
	v_fma_mix_f32 v16, v10, v36, 0 op_sel:[0,0,0] op_sel_hi:[0,1,0]
	v_fma_mix_f32 v17, v11, v36, 0 op_sel:[0,1,0] op_sel_hi:[0,1,0]
	v_add_f32_dpp v20, v14, v14 quad_perm:[1,0,3,2] row_mask:0xf bank_mask:0xf bound_ctrl:1
	v_fma_mix_f32 v60, v13, v33, v60 op_sel:[0,1,0] op_sel_hi:[0,1,0]
	v_fma_mix_f32 v18, v12, v37, 0 op_sel:[0,0,0] op_sel_hi:[0,1,0]
	v_add_f32_dpp v20, v20, v20 quad_perm:[2,3,0,1] row_mask:0xf bank_mask:0xf bound_ctrl:1
	v_fma_mix_f32 v19, v13, v37, 0 op_sel:[0,1,0] op_sel_hi:[0,1,0]
	v_fma_mix_f32 v16, v46, v42, v16 op_sel:[0,0,0] op_sel_hi:[1,1,0]
	v_add_f32_dpp v20, v20, v20 row_half_mirror row_mask:0xf bank_mask:0xf bound_ctrl:1
	v_fma_mix_f32 v17, v46, v42, v17 op_sel:[0,1,0] op_sel_hi:[1,1,0]
	v_fma_mix_f32 v18, v46, v43, v18 op_sel:[0,0,0] op_sel_hi:[1,1,0]
	v_add_f32_dpp v20, v20, v20 row_mirror row_mask:0xf bank_mask:0xf bound_ctrl:1
	v_fma_mix_f32 v19, v46, v43, v19 op_sel:[0,1,0] op_sel_hi:[1,1,0]
	v_fma_mix_f32 v10, v20, v40, v16 op_sel:[0,0,0] op_sel_hi:[0,1,0]
	v_fma_mix_f32 v11, v20, v40, v17 op_sel:[0,1,0] op_sel_hi:[0,1,0]
	v_fma_mix_f32 v12, v20, v41, v18 op_sel:[0,0,0] op_sel_hi:[0,1,0]
	v_fma_mix_f32 v13, v20, v41, v19 op_sel:[0,1,0] op_sel_hi:[0,1,0]
	s_waitcnt lgkmcnt(4)
	v_add_u32_e32 v6, 0x4000, v6
	v_add_u32_e32 v7, 0x4000, v7
	v_and_b32_e32 v6, 0x1ffff, v6
	v_and_b32_e32 v7, 0x1ffff, v7
	ds_read_b64 v[24:25], v6 offset:16
	ds_read_b128 v[26:29], v6 offset:272
	ds_read_b128 v[30:33], v6 offset:528
	ds_read_u16 v34, v7 offset:16
	v_fma_mix_f32 v14, v10, v74, 0 op_sel:[0,0,0] op_sel_hi:[0,1,0]
	v_fma_mix_f32 v61, v10, v44, 0 op_sel:[0,0,0] op_sel_hi:[0,1,0]
	v_fma_mix_f32 v14, v11, v74, v14 op_sel:[0,1,0] op_sel_hi:[0,1,0]
	v_fma_mix_f32 v61, v11, v44, v61 op_sel:[0,1,0] op_sel_hi:[0,1,0]
	v_fma_mix_f32 v14, v12, v75, v14 op_sel:[0,0,0] op_sel_hi:[0,1,0]
	v_fma_mix_f32 v61, v12, v45, v61 op_sel:[0,0,0] op_sel_hi:[0,1,0]
	v_fma_mix_f32 v14, v13, v75, v14 op_sel:[0,1,0] op_sel_hi:[0,1,0]
	v_fma_mix_f32 v16, v10, v72, 0 op_sel:[0,0,0] op_sel_hi:[0,1,0]
	v_fma_mix_f32 v17, v11, v72, 0 op_sel:[0,1,0] op_sel_hi:[0,1,0]
	v_add_f32_dpp v20, v14, v14 quad_perm:[1,0,3,2] row_mask:0xf bank_mask:0xf bound_ctrl:1
	v_fma_mix_f32 v61, v13, v45, v61 op_sel:[0,1,0] op_sel_hi:[0,1,0]
	v_fma_mix_f32 v18, v12, v73, 0 op_sel:[0,0,0] op_sel_hi:[0,1,0]
	v_add_f32_dpp v20, v20, v20 quad_perm:[2,3,0,1] row_mask:0xf bank_mask:0xf bound_ctrl:1
	v_fma_mix_f32 v19, v13, v73, 0 op_sel:[0,1,0] op_sel_hi:[0,1,0]
	v_fma_mix_f32 v16, v82, v78, v16 op_sel:[0,0,0] op_sel_hi:[1,1,0]
	v_add_f32_dpp v20, v20, v20 row_half_mirror row_mask:0xf bank_mask:0xf bound_ctrl:1
	v_fma_mix_f32 v17, v82, v78, v17 op_sel:[0,1,0] op_sel_hi:[1,1,0]
	v_fma_mix_f32 v18, v82, v79, v18 op_sel:[0,0,0] op_sel_hi:[1,1,0]
	v_add_f32_dpp v20, v20, v20 row_mirror row_mask:0xf bank_mask:0xf bound_ctrl:1
	v_fma_mix_f32 v19, v82, v79, v19 op_sel:[0,1,0] op_sel_hi:[1,1,0]
	v_fma_mix_f32 v10, v20, v76, v16 op_sel:[0,0,0] op_sel_hi:[0,1,0]
	v_fma_mix_f32 v11, v20, v76, v17 op_sel:[0,1,0] op_sel_hi:[0,1,0]
	v_fma_mix_f32 v12, v20, v77, v18 op_sel:[0,0,0] op_sel_hi:[0,1,0]
	v_fma_mix_f32 v13, v20, v77, v19 op_sel:[0,1,0] op_sel_hi:[0,1,0]
	s_waitcnt lgkmcnt(4)
	ds_read_b64 v[36:37], v6 offset:1040
	ds_read_b128 v[38:41], v6 offset:1296
	ds_read_b128 v[42:45], v6 offset:1552
	ds_read_u16 v46, v7 offset:1040
	v_fma_mix_f32 v14, v10, v86, 0 op_sel:[0,0,0] op_sel_hi:[0,1,0]
	v_fma_mix_f32 v62, v10, v80, 0 op_sel:[0,0,0] op_sel_hi:[0,1,0]
	v_fma_mix_f32 v14, v11, v86, v14 op_sel:[0,1,0] op_sel_hi:[0,1,0]
	v_fma_mix_f32 v62, v11, v80, v62 op_sel:[0,1,0] op_sel_hi:[0,1,0]
	v_fma_mix_f32 v14, v12, v87, v14 op_sel:[0,0,0] op_sel_hi:[0,1,0]
	v_fma_mix_f32 v62, v12, v81, v62 op_sel:[0,0,0] op_sel_hi:[0,1,0]
	v_fma_mix_f32 v14, v13, v87, v14 op_sel:[0,1,0] op_sel_hi:[0,1,0]
	v_fma_mix_f32 v16, v10, v84, 0 op_sel:[0,0,0] op_sel_hi:[0,1,0]
	v_fma_mix_f32 v17, v11, v84, 0 op_sel:[0,1,0] op_sel_hi:[0,1,0]
	v_add_f32_dpp v20, v14, v14 quad_perm:[1,0,3,2] row_mask:0xf bank_mask:0xf bound_ctrl:1
	v_fma_mix_f32 v62, v13, v81, v62 op_sel:[0,1,0] op_sel_hi:[0,1,0]
	v_fma_mix_f32 v18, v12, v85, 0 op_sel:[0,0,0] op_sel_hi:[0,1,0]
	v_add_f32_dpp v20, v20, v20 quad_perm:[2,3,0,1] row_mask:0xf bank_mask:0xf bound_ctrl:1
	v_fma_mix_f32 v19, v13, v85, 0 op_sel:[0,1,0] op_sel_hi:[0,1,0]
	v_fma_mix_f32 v16, v94, v90, v16 op_sel:[0,0,0] op_sel_hi:[1,1,0]
	v_add_f32_dpp v20, v20, v20 row_half_mirror row_mask:0xf bank_mask:0xf bound_ctrl:1
	v_fma_mix_f32 v17, v94, v90, v17 op_sel:[0,1,0] op_sel_hi:[1,1,0]
	v_fma_mix_f32 v18, v94, v91, v18 op_sel:[0,0,0] op_sel_hi:[1,1,0]
	v_add_f32_dpp v20, v20, v20 row_mirror row_mask:0xf bank_mask:0xf bound_ctrl:1
	v_fma_mix_f32 v19, v94, v91, v19 op_sel:[0,1,0] op_sel_hi:[1,1,0]
	v_fma_mix_f32 v10, v20, v88, v16 op_sel:[0,0,0] op_sel_hi:[0,1,0]
	v_fma_mix_f32 v11, v20, v88, v17 op_sel:[0,1,0] op_sel_hi:[0,1,0]
	v_fma_mix_f32 v12, v20, v89, v18 op_sel:[0,0,0] op_sel_hi:[0,1,0]
	v_fma_mix_f32 v13, v20, v89, v19 op_sel:[0,1,0] op_sel_hi:[0,1,0]
	s_waitcnt lgkmcnt(4)
	s_add_u32 s15, s15, 1
	s_add_u32 s14, s14, 1
	v_mov_b32_e32 v69, s15
	ds_write_b32 v68, v69
	s_cmp_lt_u32 s14, 0x100
	s_cbranch_scc1 .Lrw_blk_d0
; DEVINL u16 f2bf(float a) { return (u16)(pk2(a, 0.f) & 0xffffu); }
; #define RW_STEP2(B) RW_STEP(B, WvA, XA, KrA, vhA, WvB, XB, KrB, vhB); RW_STEP((B) + 1, WvB, XB, KrB, vhB, WvA, XA, KrA, vhA)
; #define RW_STEP4(B) RW_STEP2(B); RW_STEP2((B) + 2)
; template <int DIR>
; DEVINL void rwkv_scan_dir(const Params& p, int task, int lane, int wave) {
;     ...
;     { const int q0 = st + seg; yo[(long)(DIR ? (4095 - q0) : q0) * 1024] = f2bf(ykeep); }
;     RW_STEP(17, WvB, XB, KrB, vhB, WvA, XA, KrA, vhA);
;     RW_STEP2(18); RW_STEP4(20); RW_STEP4(24); RW_STEP4(28);
;   }
;   {
;     const float ylast = allred16(ypart);
;     ykeep = (seg == 15) ? ylast : ykeep;
;     const int q0 = 4096 - 16 + seg; yo[(long)(DIR ? (4095 - q0) : q0) * 1024] = f2bf(ykeep);
;   }
	v_fma_mix_f32 v21, v10, v92, 0 op_sel:[0,0,0] op_sel_hi:[0,1,0]
	v_fma_mix_f32 v22, v12, v93, 0 op_sel:[0,0,0] op_sel_hi:[0,1,0]
	v_fma_mix_f32 v21, v11, v92, v21 op_sel:[0,1,0] op_sel_hi:[0,1,0]
	v_fma_mix_f32 v22, v13, v93, v22 op_sel:[0,1,0] op_sel_hi:[0,1,0]
	v_add_f32_e32 v63, v21, v22
	s_nop 1
	v_add_f32_dpp v48, v48, v48 row_ror:8 row_mask:0xf bank_mask:0x3
	v_add_f32_dpp v49, v49, v49 row_ror:8 row_mask:0xf bank_mask:0x3
	v_add_f32_dpp v50, v50, v50 row_ror:8 row_mask:0xf bank_mask:0x3
	v_add_f32_dpp v51, v51, v51 row_ror:8 row_mask:0xf bank_mask:0x3
	v_add_f32_dpp v52, v52, v52 row_ror:8 row_mask:0xf bank_mask:0x3
	v_add_f32_dpp v53, v53, v53 row_ror:8 row_mask:0xf bank_mask:0x3
	v_add_f32_dpp v54, v54, v54 row_ror:8 row_mask:0xf bank_mask:0x3
	v_add_f32_dpp v55, v55, v55 row_ror:8 row_mask:0xf bank_mask:0x3
	v_add_f32_dpp v48, v56, v56 row_ror:8 row_mask:0xf bank_mask:0xc
	v_add_f32_dpp v49, v57, v57 row_ror:8 row_mask:0xf bank_mask:0xc
	v_add_f32_dpp v50, v58, v58 row_ror:8 row_mask:0xf bank_mask:0xc
	v_add_f32_dpp v51, v59, v59 row_ror:8 row_mask:0xf bank_mask:0xc
	v_add_f32_dpp v52, v60, v60 row_ror:8 row_mask:0xf bank_mask:0xc
	v_add_f32_dpp v53, v61, v61 row_ror:8 row_mask:0xf bank_mask:0xc
	v_add_f32_dpp v54, v62, v62 row_ror:8 row_mask:0xf bank_mask:0xc
	v_add_f32_dpp v55, v63, v63 row_ror:8 row_mask:0xf bank_mask:0xc
	v_add_f32_dpp v48, v48, v48 row_ror:12 row_mask:0xf bank_mask:0x5
	v_add_f32_dpp v49, v49, v49 row_ror:12 row_mask:0xf bank_mask:0x5
	v_add_f32_dpp v50, v50, v50 row_ror:12 row_mask:0xf bank_mask:0x5
	v_add_f32_dpp v51, v51, v51 row_ror:12 row_mask:0xf bank_mask:0x5
	v_add_f32_dpp v48, v52, v52 row_ror:4 row_mask:0xf bank_mask:0xa
	v_add_f32_dpp v49, v53, v53 row_ror:4 row_mask:0xf bank_mask:0xa
	v_add_f32_dpp v50, v54, v54 row_ror:4 row_mask:0xf bank_mask:0xa
	v_add_f32_dpp v51, v55, v55 row_ror:4 row_mask:0xf bank_mask:0xa
	v_add_f32_dpp v64, v48, v48 quad_perm:[2,3,0,1] row_mask:0xf bank_mask:0xf bound_ctrl:1
	v_add_f32_dpp v65, v50, v50 quad_perm:[2,3,0,1] row_mask:0xf bank_mask:0xf bound_ctrl:1
	v_cndmask_b32_e64 v56, v64, v65, s[50:51]
	v_add_f32_dpp v64, v49, v49 quad_perm:[2,3,0,1] row_mask:0xf bank_mask:0xf bound_ctrl:1
	v_add_f32_dpp v65, v51, v51 quad_perm:[2,3,0,1] row_mask:0xf bank_mask:0xf bound_ctrl:1
	v_cndmask_b32_e64 v57, v64, v65, s[50:51]
	v_add_f32_dpp v64, v56, v56 quad_perm:[1,0,3,2] row_mask:0xf bank_mask:0xf bound_ctrl:1
	s_nop 0
	v_add_f32_dpp v65, v57, v57 quad_perm:[1,0,3,2] row_mask:0xf bank_mask:0xf bound_ctrl:1
	v_cndmask_b32_e64 v66, v64, v65, s[48:49]
	v_cvt_pk_bf16_f32 v66, v66, v66
	global_store_short v8, v66, s[12:13]
	s_add_u32 s12, s12, 0x8000
	s_addc_u32 s13, s13, 0
	s_branch .Lrw_next

; DEVINL u16 f2bf(float a) { return (u16)(pk2(a, 0.f) & 0xffffu); }
; #define RW_STEP2(B) RW_STEP(B, WvA, XA, KrA, vhA, WvB, XB, KrB, vhB); RW_STEP((B) + 1, WvB, XB, KrB, vhB, WvA, XA, KrA, vhA)
; #define RW_STEP4(B) RW_STEP2(B); RW_STEP2((B) + 2)
; template <int DIR>
; DEVINL void rwkv_scan_dir(const Params& p, int task, int lane, int wave) {
;     ...
;     if (st > 0) { const int q0 = st - 16 + seg; yo[(long)(DIR ? (4095 - q0) : q0) * 1024] = f2bf(ykeep); }
;     RW_STEP(1, WvB, XB, KrB, vhB, WvA, XA, KrA, vhA);
;     RW_STEP2(2); RW_STEP4(4); RW_STEP4(8); RW_STEP4(12);
;     RW_STEP(16, WvA, XA, KrA, vhA, WvB, XB, KrB, vhB);
;     { const int q0 = st + seg; yo[(long)(DIR ? (4095 - q0) : q0) * 1024] = f2bf(ykeep); }
.Lrw_ready_d1:
	s_add_u32 s3, s40, s41
	s_and_b32 s3, s3, 0x1ffff
	s_add_u32 s3, s3, 16
	s_mov_b32 m0, s3
	s_nop 0
	global_load_lds_dwordx4 v5, s[10:11] offset:0
	global_load_lds_dwordx4 v5, s[10:11] offset:1024
	global_load_lds_dwordx4 v5, s[10:11] offset:2048
	global_load_lds_dwordx4 v5, s[10:11] offset:3072
	s_sub_u32 s10, s10, 0x4000
	s_subb_u32 s11, s11, 0
	s_sub_u32 s41, s41, 0x4000
	s_and_b32 s41, s41, 0x1ffff
	ds_read_b64 v[72:73], v6 offset:13336
	ds_read_b128 v[74:77], v6 offset:13584
	ds_read_b128 v[78:81], v6 offset:13840
	ds_read_u16 v82, v7 offset:13328
	v_fma_mix_f32 v14, v10, v26, 0 op_sel:[0,0,0] op_sel_hi:[0,1,0]
	v_fma_mix_f32 v63, v10, v92, 0 op_sel:[0,0,0] op_sel_hi:[0,1,0]
	v_fma_mix_f32 v14, v11, v26, v14 op_sel:[0,1,0] op_sel_hi:[0,1,0]
	v_fma_mix_f32 v63, v11, v92, v63 op_sel:[0,1,0] op_sel_hi:[0,1,0]
	v_fma_mix_f32 v14, v12, v27, v14 op_sel:[0,0,0] op_sel_hi:[0,1,0]
	v_fma_mix_f32 v63, v12, v93, v63 op_sel:[0,0,0] op_sel_hi:[0,1,0]
	v_fma_mix_f32 v14, v13, v27, v14 op_sel:[0,1,0] op_sel_hi:[0,1,0]
	v_fma_mix_f32 v16, v10, v24, 0 op_sel:[0,0,0] op_sel_hi:[0,1,0]
	v_fma_mix_f32 v17, v11, v24, 0 op_sel:[0,1,0] op_sel_hi:[0,1,0]
	v_add_f32_dpp v20, v14, v14 quad_perm:[1,0,3,2] row_mask:0xf bank_mask:0xf bound_ctrl:1
	v_fma_mix_f32 v63, v13, v93, v63 op_sel:[0,1,0] op_sel_hi:[0,1,0]
	v_fma_mix_f32 v18, v12, v25, 0 op_sel:[0,0,0] op_sel_hi:[0,1,0]
	v_add_f32_dpp v20, v20, v20 quad_perm:[2,3,0,1] row_mask:0xf bank_mask:0xf bound_ctrl:1
	v_fma_mix_f32 v19, v13, v25, 0 op_sel:[0,1,0] op_sel_hi:[0,1,0]
	v_fma_mix_f32 v16, v34, v30, v16 op_sel:[0,0,0] op_sel_hi:[1,1,0]
	v_add_f32_dpp v20, v20, v20 row_half_mirror row_mask:0xf bank_mask:0xf bound_ctrl:1
	v_fma_mix_f32 v17, v34, v30, v17 op_sel:[0,1,0] op_sel_hi:[1,1,0]
	v_fma_mix_f32 v18, v34, v31, v18 op_sel:[0,0,0] op_sel_hi:[1,1,0]
	v_add_f32_dpp v20, v20, v20 row_mirror row_mask:0xf bank_mask:0xf bound_ctrl:1
	v_fma_mix_f32 v19, v34, v31, v19 op_sel:[0,1,0] op_sel_hi:[1,1,0]
	v_fma_mix_f32 v10, v20, v28, v16 op_sel:[0,0,0] op_sel_hi:[0,1,0]
	v_fma_mix_f32 v11, v20, v28, v17 op_sel:[0,1,0] op_sel_hi:[0,1,0]
	v_fma_mix_f32 v12, v20, v29, v18 op_sel:[0,0,0] op_sel_hi:[0,1,0]
	v_fma_mix_f32 v13, v20, v29, v19 op_sel:[0,1,0] op_sel_hi:[0,1,0]
	s_waitcnt lgkmcnt(4)
	s_cmp_eq_u32 s14, 0
	s_cbranch_scc1 .Lrw_skip_d1
	v_add_f32_dpp v48, v48, v48 row_ror:8 row_mask:0xf bank_mask:0x3
	v_add_f32_dpp v49, v49, v49 row_ror:8 row_mask:0xf bank_mask:0x3
	v_add_f32_dpp v50, v50, v50 row_ror:8 row_mask:0xf bank_mask:0x3
	v_add_f32_dpp v51, v51, v51 row_ror:8 row_mask:0xf bank_mask:0x3
	v_add_f32_dpp v52, v52, v52 row_ror:8 row_mask:0xf bank_mask:0x3
	v_add_f32_dpp v53, v53, v53 row_ror:8 row_mask:0xf bank_mask:0x3
	v_add_f32_dpp v54, v54, v54 row_ror:8 row_mask:0xf bank_mask:0x3
	v_add_f32_dpp v55, v55, v55 row_ror:8 row_mask:0xf bank_mask:0x3
	v_add_f32_dpp v48, v56, v56 row_ror:8 row_mask:0xf bank_mask:0xc
	v_add_f32_dpp v49, v57, v57 row_ror:8 row_mask:0xf bank_mask:0xc
	v_add_f32_dpp v50, v58, v58 row_ror:8 row_mask:0xf bank_mask:0xc
	v_add_f32_dpp v51, v59, v59 row_ror:8 row_mask:0xf bank_mask:0xc
	v_add_f32_dpp v52, v60, v60 row_ror:8 row_mask:0xf bank_mask:0xc
	v_add_f32_dpp v53, v61, v61 row_ror:8 row_mask:0xf bank_mask:0xc
	v_add_f32_dpp v54, v62, v62 row_ror:8 row_mask:0xf bank_mask:0xc
	v_add_f32_dpp v55, v63, v63 row_ror:8 row_mask:0xf bank_mask:0xc
	v_add_f32_dpp v48, v48, v48 row_ror:12 row_mask:0xf bank_mask:0x5
	v_add_f32_dpp v49, v49, v49 row_ror:12 row_mask:0xf bank_mask:0x5
	v_add_f32_dpp v50, v50, v50 row_ror:12 row_mask:0xf bank_mask:0x5
	v_add_f32_dpp v51, v51, v51 row_ror:12 row_mask:0xf bank_mask:0x5
	v_add_f32_dpp v48, v52, v52 row_ror:4 row_mask:0xf bank_mask:0xa
	v_add_f32_dpp v49, v53, v53 row_ror:4 row_mask:0xf bank_mask:0xa
	v_add_f32_dpp v50, v54, v54 row_ror:4 row_mask:0xf bank_mask:0xa
	v_add_f32_dpp v51, v55, v55 row_ror:4 row_mask:0xf bank_mask:0xa
	v_add_f32_dpp v64, v48, v48 quad_perm:[2,3,0,1] row_mask:0xf bank_mask:0xf bound_ctrl:1
	v_add_f32_dpp v65, v50, v50 quad_perm:[2,3,0,1] row_mask:0xf bank_mask:0xf bound_ctrl:1
	v_cndmask_b32_e64 v56, v64, v65, s[50:51]
	v_add_f32_dpp v64, v49, v49 quad_perm:[2,3,0,1] row_mask:0xf bank_mask:0xf bound_ctrl:1
	v_add_f32_dpp v65, v51, v51 quad_perm:[2,3,0,1] row_mask:0xf bank_mask:0xf bound_ctrl:1
	v_cndmask_b32_e64 v57, v64, v65, s[50:51]
	v_add_f32_dpp v64, v56, v56 quad_perm:[1,0,3,2] row_mask:0xf bank_mask:0xf bound_ctrl:1
	s_nop 0
	v_add_f32_dpp v65, v57, v57 quad_perm:[1,0,3,2] row_mask:0xf bank_mask:0xf bound_ctrl:1
	v_cndmask_b32_e64 v66, v64, v65, s[48:49]
	v_cvt_pk_bf16_f32 v66, v66, v66
	global_store_short v8, v66, s[12:13]
	s_sub_u32 s12, s12, 0x8000
	s_subb_u32 s13, s13, 0
.Lrw_skip_d1:
	ds_read_b64 v[84:85], v6 offset:12312
	ds_read_b128 v[86:89], v6 offset:12560
	ds_read_b128 v[90:93], v6 offset:12816
	ds_read_u16 v94, v7 offset:12304
	v_fma_mix_f32 v14, v10, v38, 0 op_sel:[0,0,0] op_sel_hi:[0,1,0]
	v_fma_mix_f32 v48, v10, v32, 0 op_sel:[0,0,0] op_sel_hi:[0,1,0]
	v_fma_mix_f32 v14, v11, v38, v14 op_sel:[0,1,0] op_sel_hi:[0,1,0]
	v_fma_mix_f32 v48, v11, v32, v48 op_sel:[0,1,0] op_sel_hi:[0,1,0]
	v_fma_mix_f32 v14, v12, v39, v14 op_sel:[0,0,0] op_sel_hi:[0,1,0]
	v_fma_mix_f32 v48, v12, v33, v48 op_sel:[0,0,0] op_sel_hi:[0,1,0]
	v_fma_mix_f32 v14, v13, v39, v14 op_sel:[0,1,0] op_sel_hi:[0,1,0]
	v_fma_mix_f32 v16, v10, v36, 0 op_sel:[0,0,0] op_sel_hi:[0,1,0]
	v_fma_mix_f32 v17, v11, v36, 0 op_sel:[0,1,0] op_sel_hi:[0,1,0]
	v_add_f32_dpp v20, v14, v14 quad_perm:[1,0,3,2] row_mask:0xf bank_mask:0xf bound_ctrl:1
	v_fma_mix_f32 v48, v13, v33, v48 op_sel:[0,1,0] op_sel_hi:[0,1,0]
	v_fma_mix_f32 v18, v12, v37, 0 op_sel:[0,0,0] op_sel_hi:[0,1,0]
	v_add_f32_dpp v20, v20, v20 quad_perm:[2,3,0,1] row_mask:0xf bank_mask:0xf bound_ctrl:1
	v_fma_mix_f32 v19, v13, v37, 0 op_sel:[0,1,0] op_sel_hi:[0,1,0]
	v_fma_mix_f32 v16, v46, v42, v16 op_sel:[0,0,0] op_sel_hi:[1,1,0]
	v_add_f32_dpp v20, v20, v20 row_half_mirror row_mask:0xf bank_mask:0xf bound_ctrl:1
	v_fma_mix_f32 v17, v46, v42, v17 op_sel:[0,1,0] op_sel_hi:[1,1,0]
	v_fma_mix_f32 v18, v46, v43, v18 op_sel:[0,0,0] op_sel_hi:[1,1,0]
	v_add_f32_dpp v20, v20, v20 row_mirror row_mask:0xf bank_mask:0xf bound_ctrl:1
	v_fma_mix_f32 v19, v46, v43, v19 op_sel:[0,1,0] op_sel_hi:[1,1,0]
	v_fma_mix_f32 v10, v20, v40, v16 op_sel:[0,0,0] op_sel_hi:[0,1,0]
	v_fma_mix_f32 v11, v20, v40, v17 op_sel:[0,1,0] op_sel_hi:[0,1,0]
	v_fma_mix_f32 v12, v20, v41, v18 op_sel:[0,0,0] op_sel_hi:[0,1,0]
	v_fma_mix_f32 v13, v20, v41, v19 op_sel:[0,1,0] op_sel_hi:[0,1,0]
	s_waitcnt lgkmcnt(4)
	ds_read_b64 v[24:25], v6 offset:11288
	ds_read_b128 v[26:29], v6 offset:11536
	ds_read_b128 v[30:33], v6 offset:11792
	ds_read_u16 v34, v7 offset:11280
	v_fma_mix_f32 v14, v10, v74, 0 op_sel:[0,0,0] op_sel_hi:[0,1,0]
	v_fma_mix_f32 v49, v10, v44, 0 op_sel:[0,0,0] op_sel_hi:[0,1,0]
	v_fma_mix_f32 v14, v11, v74, v14 op_sel:[0,1,0] op_sel_hi:[0,1,0]
	v_fma_mix_f32 v49, v11, v44, v49 op_sel:[0,1,0] op_sel_hi:[0,1,0]
	v_fma_mix_f32 v14, v12, v75, v14 op_sel:[0,0,0] op_sel_hi:[0,1,0]
	v_fma_mix_f32 v49, v12, v45, v49 op_sel:[0,0,0] op_sel_hi:[0,1,0]
	v_fma_mix_f32 v14, v13, v75, v14 op_sel:[0,1,0] op_sel_hi:[0,1,0]
	v_fma_mix_f32 v16, v10, v72, 0 op_sel:[0,0,0] op_sel_hi:[0,1,0]
	v_fma_mix_f32 v17, v11, v72, 0 op_sel:[0,1,0] op_sel_hi:[0,1,0]
	v_add_f32_dpp v20, v14, v14 quad_perm:[1,0,3,2] row_mask:0xf bank_mask:0xf bound_ctrl:1
	v_fma_mix_f32 v49, v13, v45, v49 op_sel:[0,1,0] op_sel_hi:[0,1,0]
	v_fma_mix_f32 v18, v12, v73, 0 op_sel:[0,0,0] op_sel_hi:[0,1,0]
	v_add_f32_dpp v20, v20, v20 quad_perm:[2,3,0,1] row_mask:0xf bank_mask:0xf bound_ctrl:1
	v_fma_mix_f32 v19, v13, v73, 0 op_sel:[0,1,0] op_sel_hi:[0,1,0]
	v_fma_mix_f32 v16, v82, v78, v16 op_sel:[0,0,0] op_sel_hi:[1,1,0]
	v_add_f32_dpp v20, v20, v20 row_half_mirror row_mask:0xf bank_mask:0xf bound_ctrl:1
	v_fma_mix_f32 v17, v82, v78, v17 op_sel:[0,1,0] op_sel_hi:[1,1,0]
	v_fma_mix_f32 v18, v82, v79, v18 op_sel:[0,0,0] op_sel_hi:[1,1,0]
	v_add_f32_dpp v20, v20, v20 row_mirror row_mask:0xf bank_mask:0xf bound_ctrl:1
	v_fma_mix_f32 v19, v82, v79, v19 op_sel:[0,1,0] op_sel_hi:[1,1,0]
	v_fma_mix_f32 v10, v20, v76, v16 op_sel:[0,0,0] op_sel_hi:[0,1,0]
	v_fma_mix_f32 v11, v20, v76, v17 op_sel:[0,1,0] op_sel_hi:[0,1,0]
	v_fma_mix_f32 v12, v20, v77, v18 op_sel:[0,0,0] op_sel_hi:[0,1,0]
	v_fma_mix_f32 v13, v20, v77, v19 op_sel:[0,1,0] op_sel_hi:[0,1,0]
	s_waitcnt lgkmcnt(4)
	ds_read_b64 v[36:37], v6 offset:10264
	ds_read_b128 v[38:41], v6 offset:10512
	ds_read_b128 v[42:45], v6 offset:10768
	ds_read_u16 v46, v7 offset:10256
	v_fma_mix_f32 v14, v10, v86, 0 op_sel:[0,0,0] op_sel_hi:[0,1,0]
	v_fma_mix_f32 v50, v10, v80, 0 op_sel:[0,0,0] op_sel_hi:[0,1,0]
	v_fma_mix_f32 v14, v11, v86, v14 op_sel:[0,1,0] op_sel_hi:[0,1,0]
	v_fma_mix_f32 v50, v11, v80, v50 op_sel:[0,1,0] op_sel_hi:[0,1,0]
	v_fma_mix_f32 v14, v12, v87, v14 op_sel:[0,0,0] op_sel_hi:[0,1,0]
	v_fma_mix_f32 v50, v12, v81, v50 op_sel:[0,0,0] op_sel_hi:[0,1,0]
	v_fma_mix_f32 v14, v13, v87, v14 op_sel:[0,1,0] op_sel_hi:[0,1,0]
	v_fma_mix_f32 v16, v10, v84, 0 op_sel:[0,0,0] op_sel_hi:[0,1,0]
	v_fma_mix_f32 v17, v11, v84, 0 op_sel:[0,1,0] op_sel_hi:[0,1,0]
	v_add_f32_dpp v20, v14, v14 quad_perm:[1,0,3,2] row_mask:0xf bank_mask:0xf bound_ctrl:1
	v_fma_mix_f32 v50, v13, v81, v50 op_sel:[0,1,0] op_sel_hi:[0,1,0]
	v_fma_mix_f32 v18, v12, v85, 0 op_sel:[0,0,0] op_sel_hi:[0,1,0]
	v_add_f32_dpp v20, v20, v20 quad_perm:[2,3,0,1] row_mask:0xf bank_mask:0xf bound_ctrl:1
	v_fma_mix_f32 v19, v13, v85, 0 op_sel:[0,1,0] op_sel_hi:[0,1,0]
	v_fma_mix_f32 v16, v94, v90, v16 op_sel:[0,0,0] op_sel_hi:[1,1,0]
	v_add_f32_dpp v20, v20, v20 row_half_mirror row_mask:0xf bank_mask:0xf bound_ctrl:1
	v_fma_mix_f32 v17, v94, v90, v17 op_sel:[0,1,0] op_sel_hi:[1,1,0]
	v_fma_mix_f32 v18, v94, v91, v18 op_sel:[0,0,0] op_sel_hi:[1,1,0]
	v_add_f32_dpp v20, v20, v20 row_mirror row_mask:0xf bank_mask:0xf bound_ctrl:1
	v_fma_mix_f32 v19, v94, v91, v19 op_sel:[0,1,0] op_sel_hi:[1,1,0]
	v_fma_mix_f32 v10, v20, v88, v16 op_sel:[0,0,0] op_sel_hi:[0,1,0]
	v_fma_mix_f32 v11, v20, v88, v17 op_sel:[0,1,0] op_sel_hi:[0,1,0]
	v_fma_mix_f32 v12, v20, v89, v18 op_sel:[0,0,0] op_sel_hi:[0,1,0]
	v_fma_mix_f32 v13, v20, v89, v19 op_sel:[0,1,0] op_sel_hi:[0,1,0]
	s_waitcnt lgkmcnt(4)
	ds_read_b64 v[72:73], v6 offset:9240
	ds_read_b128 v[74:77], v6 offset:9488
	ds_read_b128 v[78:81], v6 offset:9744
	ds_read_u16 v82, v7 offset:9232
	v_fma_mix_f32 v14, v10, v26, 0 op_sel:[0,0,0] op_sel_hi:[0,1,0]
	v_fma_mix_f32 v51, v10, v92, 0 op_sel:[0,0,0] op_sel_hi:[0,1,0]
	v_fma_mix_f32 v14, v11, v26, v14 op_sel:[0,1,0] op_sel_hi:[0,1,0]
	v_fma_mix_f32 v51, v11, v92, v51 op_sel:[0,1,0] op_sel_hi:[0,1,0]
	v_fma_mix_f32 v14, v12, v27, v14 op_sel:[0,0,0] op_sel_hi:[0,1,0]
	v_fma_mix_f32 v51, v12, v93, v51 op_sel:[0,0,0] op_sel_hi:[0,1,0]
	v_fma_mix_f32 v14, v13, v27, v14 op_sel:[0,1,0] op_sel_hi:[0,1,0]
	v_fma_mix_f32 v16, v10, v24, 0 op_sel:[0,0,0] op_sel_hi:[0,1,0]
	v_fma_mix_f32 v17, v11, v24, 0 op_sel:[0,1,0] op_sel_hi:[0,1,0]
	v_add_f32_dpp v20, v14, v14 quad_perm:[1,0,3,2] row_mask:0xf bank_mask:0xf bound_ctrl:1
	v_fma_mix_f32 v51, v13, v93, v51 op_sel:[0,1,0] op_sel_hi:[0,1,0]
	v_fma_mix_f32 v18, v12, v25, 0 op_sel:[0,0,0] op_sel_hi:[0,1,0]
	v_add_f32_dpp v20, v20, v20 quad_perm:[2,3,0,1] row_mask:0xf bank_mask:0xf bound_ctrl:1
	v_fma_mix_f32 v19, v13, v25, 0 op_sel:[0,1,0] op_sel_hi:[0,1,0]
	v_fma_mix_f32 v16, v34, v30, v16 op_sel:[0,0,0] op_sel_hi:[1,1,0]
	v_add_f32_dpp v20, v20, v20 row_half_mirror row_mask:0xf bank_mask:0xf bound_ctrl:1
	v_fma_mix_f32 v17, v34, v30, v17 op_sel:[0,1,0] op_sel_hi:[1,1,0]
	v_fma_mix_f32 v18, v34, v31, v18 op_sel:[0,0,0] op_sel_hi:[1,1,0]
	v_add_f32_dpp v20, v20, v20 row_mirror row_mask:0xf bank_mask:0xf bound_ctrl:1
	v_fma_mix_f32 v19, v34, v31, v19 op_sel:[0,1,0] op_sel_hi:[1,1,0]
	v_fma_mix_f32 v10, v20, v28, v16 op_sel:[0,0,0] op_sel_hi:[0,1,0]
	v_fma_mix_f32 v11, v20, v28, v17 op_sel:[0,1,0] op_sel_hi:[0,1,0]
	v_fma_mix_f32 v12, v20, v29, v18 op_sel:[0,0,0] op_sel_hi:[0,1,0]
	v_fma_mix_f32 v13, v20, v29, v19 op_sel:[0,1,0] op_sel_hi:[0,1,0]
	s_waitcnt lgkmcnt(4)
	ds_read_b64 v[84:85], v6 offset:8216
	ds_read_b128 v[86:89], v6 offset:8464
	ds_read_b128 v[90:93], v6 offset:8720
	ds_read_u16 v94, v7 offset:8208
	v_fma_mix_f32 v14, v10, v38, 0 op_sel:[0,0,0] op_sel_hi:[0,1,0]
	v_fma_mix_f32 v52, v10, v32, 0 op_sel:[0,0,0] op_sel_hi:[0,1,0]
	v_fma_mix_f32 v14, v11, v38, v14 op_sel:[0,1,0] op_sel_hi:[0,1,0]
	v_fma_mix_f32 v52, v11, v32, v52 op_sel:[0,1,0] op_sel_hi:[0,1,0]
	v_fma_mix_f32 v14, v12, v39, v14 op_sel:[0,0,0] op_sel_hi:[0,1,0]
	v_fma_mix_f32 v52, v12, v33, v52 op_sel:[0,0,0] op_sel_hi:[0,1,0]
	v_fma_mix_f32 v14, v13, v39, v14 op_sel:[0,1,0] op_sel_hi:[0,1,0]
	v_fma_mix_f32 v16, v10, v36, 0 op_sel:[0,0,0] op_sel_hi:[0,1,0]
	v_fma_mix_f32 v17, v11, v36, 0 op_sel:[0,1,0] op_sel_hi:[0,1,0]
	v_add_f32_dpp v20, v14, v14 quad_perm:[1,0,3,2] row_mask:0xf bank_mask:0xf bound_ctrl:1
	v_fma_mix_f32 v52, v13, v33, v52 op_sel:[0,1,0] op_sel_hi:[0,1,0]
	v_fma_mix_f32 v18, v12, v37, 0 op_sel:[0,0,0] op_sel_hi:[0,1,0]
	v_add_f32_dpp v20, v20, v20 quad_perm:[2,3,0,1] row_mask:0xf bank_mask:0xf bound_ctrl:1
	v_fma_mix_f32 v19, v13, v37, 0 op_sel:[0,1,0] op_sel_hi:[0,1,0]
	v_fma_mix_f32 v16, v46, v42, v16 op_sel:[0,0,0] op_sel_hi:[1,1,0]
	v_add_f32_dpp v20, v20, v20 row_half_mirror row_mask:0xf bank_mask:0xf bound_ctrl:1
	v_fma_mix_f32 v17, v46, v42, v17 op_sel:[0,1,0] op_sel_hi:[1,1,0]
	v_fma_mix_f32 v18, v46, v43, v18 op_sel:[0,0,0] op_sel_hi:[1,1,0]
	v_add_f32_dpp v20, v20, v20 row_mirror row_mask:0xf bank_mask:0xf bound_ctrl:1
	v_fma_mix_f32 v19, v46, v43, v19 op_sel:[0,1,0] op_sel_hi:[1,1,0]
	v_fma_mix_f32 v10, v20, v40, v16 op_sel:[0,0,0] op_sel_hi:[0,1,0]
	v_fma_mix_f32 v11, v20, v40, v17 op_sel:[0,1,0] op_sel_hi:[0,1,0]
	v_fma_mix_f32 v12, v20, v41, v18 op_sel:[0,0,0] op_sel_hi:[0,1,0]
	v_fma_mix_f32 v13, v20, v41, v19 op_sel:[0,1,0] op_sel_hi:[0,1,0]
	s_waitcnt lgkmcnt(4)
	ds_read_b64 v[24:25], v6 offset:7192
	ds_read_b128 v[26:29], v6 offset:7440
	ds_read_b128 v[30:33], v6 offset:7696
	ds_read_u16 v34, v7 offset:7184
	v_fma_mix_f32 v14, v10, v74, 0 op_sel:[0,0,0] op_sel_hi:[0,1,0]
	v_fma_mix_f32 v53, v10, v44, 0 op_sel:[0,0,0] op_sel_hi:[0,1,0]
	v_fma_mix_f32 v14, v11, v74, v14 op_sel:[0,1,0] op_sel_hi:[0,1,0]
	v_fma_mix_f32 v53, v11, v44, v53 op_sel:[0,1,0] op_sel_hi:[0,1,0]
	v_fma_mix_f32 v14, v12, v75, v14 op_sel:[0,0,0] op_sel_hi:[0,1,0]
	v_fma_mix_f32 v53, v12, v45, v53 op_sel:[0,0,0] op_sel_hi:[0,1,0]
	v_fma_mix_f32 v14, v13, v75, v14 op_sel:[0,1,0] op_sel_hi:[0,1,0]
	v_fma_mix_f32 v16, v10, v72, 0 op_sel:[0,0,0] op_sel_hi:[0,1,0]
	v_fma_mix_f32 v17, v11, v72, 0 op_sel:[0,1,0] op_sel_hi:[0,1,0]
	v_add_f32_dpp v20, v14, v14 quad_perm:[1,0,3,2] row_mask:0xf bank_mask:0xf bound_ctrl:1
	v_fma_mix_f32 v53, v13, v45, v53 op_sel:[0,1,0] op_sel_hi:[0,1,0]
	v_fma_mix_f32 v18, v12, v73, 0 op_sel:[0,0,0] op_sel_hi:[0,1,0]
	v_add_f32_dpp v20, v20, v20 quad_perm:[2,3,0,1] row_mask:0xf bank_mask:0xf bound_ctrl:1
	v_fma_mix_f32 v19, v13, v73, 0 op_sel:[0,1,0] op_sel_hi:[0,1,0]
	v_fma_mix_f32 v16, v82, v78, v16 op_sel:[0,0,0] op_sel_hi:[1,1,0]
	v_add_f32_dpp v20, v20, v20 row_half_mirror row_mask:0xf bank_mask:0xf bound_ctrl:1
	v_fma_mix_f32 v17, v82, v78, v17 op_sel:[0,1,0] op_sel_hi:[1,1,0]
	v_fma_mix_f32 v18, v82, v79, v18 op_sel:[0,0,0] op_sel_hi:[1,1,0]
	v_add_f32_dpp v20, v20, v20 row_mirror row_mask:0xf bank_mask:0xf bound_ctrl:1
	v_fma_mix_f32 v19, v82, v79, v19 op_sel:[0,1,0] op_sel_hi:[1,1,0]
	v_fma_mix_f32 v10, v20, v76, v16 op_sel:[0,0,0] op_sel_hi:[0,1,0]
	v_fma_mix_f32 v11, v20, v76, v17 op_sel:[0,1,0] op_sel_hi:[0,1,0]
	v_fma_mix_f32 v12, v20, v77, v18 op_sel:[0,0,0] op_sel_hi:[0,1,0]
	v_fma_mix_f32 v13, v20, v77, v19 op_sel:[0,1,0] op_sel_hi:[0,1,0]
	s_waitcnt lgkmcnt(4)
	ds_read_b64 v[36:37], v6 offset:6168
	ds_read_b128 v[38:41], v6 offset:6416
	ds_read_b128 v[42:45], v6 offset:6672
	ds_read_u16 v46, v7 offset:6160
	v_fma_mix_f32 v14, v10, v86, 0 op_sel:[0,0,0] op_sel_hi:[0,1,0]
	v_fma_mix_f32 v54, v10, v80, 0 op_sel:[0,0,0] op_sel_hi:[0,1,0]
	v_fma_mix_f32 v14, v11, v86, v14 op_sel:[0,1,0] op_sel_hi:[0,1,0]
	v_fma_mix_f32 v54, v11, v80, v54 op_sel:[0,1,0] op_sel_hi:[0,1,0]
	v_fma_mix_f32 v14, v12, v87, v14 op_sel:[0,0,0] op_sel_hi:[0,1,0]
	v_fma_mix_f32 v54, v12, v81, v54 op_sel:[0,0,0] op_sel_hi:[0,1,0]
	v_fma_mix_f32 v14, v13, v87, v14 op_sel:[0,1,0] op_sel_hi:[0,1,0]
	v_fma_mix_f32 v16, v10, v84, 0 op_sel:[0,0,0] op_sel_hi:[0,1,0]
	v_fma_mix_f32 v17, v11, v84, 0 op_sel:[0,1,0] op_sel_hi:[0,1,0]
	v_add_f32_dpp v20, v14, v14 quad_perm:[1,0,3,2] row_mask:0xf bank_mask:0xf bound_ctrl:1
	v_fma_mix_f32 v54, v13, v81, v54 op_sel:[0,1,0] op_sel_hi:[0,1,0]
	v_fma_mix_f32 v18, v12, v85, 0 op_sel:[0,0,0] op_sel_hi:[0,1,0]
	v_add_f32_dpp v20, v20, v20 quad_perm:[2,3,0,1] row_mask:0xf bank_mask:0xf bound_ctrl:1
	v_fma_mix_f32 v19, v13, v85, 0 op_sel:[0,1,0] op_sel_hi:[0,1,0]
	v_fma_mix_f32 v16, v94, v90, v16 op_sel:[0,0,0] op_sel_hi:[1,1,0]
	v_add_f32_dpp v20, v20, v20 row_half_mirror row_mask:0xf bank_mask:0xf bound_ctrl:1
	v_fma_mix_f32 v17, v94, v90, v17 op_sel:[0,1,0] op_sel_hi:[1,1,0]
	v_fma_mix_f32 v18, v94, v91, v18 op_sel:[0,0,0] op_sel_hi:[1,1,0]
	v_add_f32_dpp v20, v20, v20 row_mirror row_mask:0xf bank_mask:0xf bound_ctrl:1
	v_fma_mix_f32 v19, v94, v91, v19 op_sel:[0,1,0] op_sel_hi:[1,1,0]
	v_fma_mix_f32 v10, v20, v88, v16 op_sel:[0,0,0] op_sel_hi:[0,1,0]
	v_fma_mix_f32 v11, v20, v88, v17 op_sel:[0,1,0] op_sel_hi:[0,1,0]
	v_fma_mix_f32 v12, v20, v89, v18 op_sel:[0,0,0] op_sel_hi:[0,1,0]
	v_fma_mix_f32 v13, v20, v89, v19 op_sel:[0,1,0] op_sel_hi:[0,1,0]
	s_waitcnt lgkmcnt(4)
	ds_read_b64 v[72:73], v6 offset:5144
	ds_read_b128 v[74:77], v6 offset:5392
	ds_read_b128 v[78:81], v6 offset:5648
	ds_read_u16 v82, v7 offset:5136
	v_fma_mix_f32 v14, v10, v26, 0 op_sel:[0,0,0] op_sel_hi:[0,1,0]
	v_fma_mix_f32 v55, v10, v92, 0 op_sel:[0,0,0] op_sel_hi:[0,1,0]
	v_fma_mix_f32 v14, v11, v26, v14 op_sel:[0,1,0] op_sel_hi:[0,1,0]
	v_fma_mix_f32 v55, v11, v92, v55 op_sel:[0,1,0] op_sel_hi:[0,1,0]
	v_fma_mix_f32 v14, v12, v27, v14 op_sel:[0,0,0] op_sel_hi:[0,1,0]
	v_fma_mix_f32 v55, v12, v93, v55 op_sel:[0,0,0] op_sel_hi:[0,1,0]
	v_fma_mix_f32 v14, v13, v27, v14 op_sel:[0,1,0] op_sel_hi:[0,1,0]
	v_fma_mix_f32 v16, v10, v24, 0 op_sel:[0,0,0] op_sel_hi:[0,1,0]
	v_fma_mix_f32 v17, v11, v24, 0 op_sel:[0,1,0] op_sel_hi:[0,1,0]
	v_add_f32_dpp v20, v14, v14 quad_perm:[1,0,3,2] row_mask:0xf bank_mask:0xf bound_ctrl:1
	v_fma_mix_f32 v55, v13, v93, v55 op_sel:[0,1,0] op_sel_hi:[0,1,0]
	v_fma_mix_f32 v18, v12, v25, 0 op_sel:[0,0,0] op_sel_hi:[0,1,0]
	v_add_f32_dpp v20, v20, v20 quad_perm:[2,3,0,1] row_mask:0xf bank_mask:0xf bound_ctrl:1
	v_fma_mix_f32 v19, v13, v25, 0 op_sel:[0,1,0] op_sel_hi:[0,1,0]
	v_fma_mix_f32 v16, v34, v30, v16 op_sel:[0,0,0] op_sel_hi:[1,1,0]
	v_add_f32_dpp v20, v20, v20 row_half_mirror row_mask:0xf bank_mask:0xf bound_ctrl:1
	v_fma_mix_f32 v17, v34, v30, v17 op_sel:[0,1,0] op_sel_hi:[1,1,0]
	v_fma_mix_f32 v18, v34, v31, v18 op_sel:[0,0,0] op_sel_hi:[1,1,0]
	v_add_f32_dpp v20, v20, v20 row_mirror row_mask:0xf bank_mask:0xf bound_ctrl:1
	v_fma_mix_f32 v19, v34, v31, v19 op_sel:[0,1,0] op_sel_hi:[1,1,0]
	v_fma_mix_f32 v10, v20, v28, v16 op_sel:[0,0,0] op_sel_hi:[0,1,0]
	v_fma_mix_f32 v11, v20, v28, v17 op_sel:[0,1,0] op_sel_hi:[0,1,0]
	v_fma_mix_f32 v12, v20, v29, v18 op_sel:[0,0,0] op_sel_hi:[0,1,0]
	v_fma_mix_f32 v13, v20, v29, v19 op_sel:[0,1,0] op_sel_hi:[0,1,0]
	s_waitcnt lgkmcnt(4)
	ds_read_b64 v[84:85], v6 offset:4120
	ds_read_b128 v[86:89], v6 offset:4368
	ds_read_b128 v[90:93], v6 offset:4624
	ds_read_u16 v94, v7 offset:4112
	v_fma_mix_f32 v14, v10, v38, 0 op_sel:[0,0,0] op_sel_hi:[0,1,0]
	v_fma_mix_f32 v56, v10, v32, 0 op_sel:[0,0,0] op_sel_hi:[0,1,0]
	v_fma_mix_f32 v14, v11, v38, v14 op_sel:[0,1,0] op_sel_hi:[0,1,0]
	v_fma_mix_f32 v56, v11, v32, v56 op_sel:[0,1,0] op_sel_hi:[0,1,0]
	v_fma_mix_f32 v14, v12, v39, v14 op_sel:[0,0,0] op_sel_hi:[0,1,0]
	v_fma_mix_f32 v56, v12, v33, v56 op_sel:[0,0,0] op_sel_hi:[0,1,0]
	v_fma_mix_f32 v14, v13, v39, v14 op_sel:[0,1,0] op_sel_hi:[0,1,0]
	v_fma_mix_f32 v16, v10, v36, 0 op_sel:[0,0,0] op_sel_hi:[0,1,0]
	v_fma_mix_f32 v17, v11, v36, 0 op_sel:[0,1,0] op_sel_hi:[0,1,0]
	v_add_f32_dpp v20, v14, v14 quad_perm:[1,0,3,2] row_mask:0xf bank_mask:0xf bound_ctrl:1
	v_fma_mix_f32 v56, v13, v33, v56 op_sel:[0,1,0] op_sel_hi:[0,1,0]
	v_fma_mix_f32 v18, v12, v37, 0 op_sel:[0,0,0] op_sel_hi:[0,1,0]
	v_add_f32_dpp v20, v20, v20 quad_perm:[2,3,0,1] row_mask:0xf bank_mask:0xf bound_ctrl:1
	v_fma_mix_f32 v19, v13, v37, 0 op_sel:[0,1,0] op_sel_hi:[0,1,0]
	v_fma_mix_f32 v16, v46, v42, v16 op_sel:[0,0,0] op_sel_hi:[1,1,0]
	v_add_f32_dpp v20, v20, v20 row_half_mirror row_mask:0xf bank_mask:0xf bound_ctrl:1
	v_fma_mix_f32 v17, v46, v42, v17 op_sel:[0,1,0] op_sel_hi:[1,1,0]
	v_fma_mix_f32 v18, v46, v43, v18 op_sel:[0,0,0] op_sel_hi:[1,1,0]
	v_add_f32_dpp v20, v20, v20 row_mirror row_mask:0xf bank_mask:0xf bound_ctrl:1
	v_fma_mix_f32 v19, v46, v43, v19 op_sel:[0,1,0] op_sel_hi:[1,1,0]
	v_fma_mix_f32 v10, v20, v40, v16 op_sel:[0,0,0] op_sel_hi:[0,1,0]
	v_fma_mix_f32 v11, v20, v40, v17 op_sel:[0,1,0] op_sel_hi:[0,1,0]
	v_fma_mix_f32 v12, v20, v41, v18 op_sel:[0,0,0] op_sel_hi:[0,1,0]
	v_fma_mix_f32 v13, v20, v41, v19 op_sel:[0,1,0] op_sel_hi:[0,1,0]
	s_waitcnt lgkmcnt(4)
	ds_read_b64 v[24:25], v6 offset:3096
	ds_read_b128 v[26:29], v6 offset:3344
	ds_read_b128 v[30:33], v6 offset:3600
	ds_read_u16 v34, v7 offset:3088
	v_fma_mix_f32 v14, v10, v74, 0 op_sel:[0,0,0] op_sel_hi:[0,1,0]
	v_fma_mix_f32 v57, v10, v44, 0 op_sel:[0,0,0] op_sel_hi:[0,1,0]
	v_fma_mix_f32 v14, v11, v74, v14 op_sel:[0,1,0] op_sel_hi:[0,1,0]
	v_fma_mix_f32 v57, v11, v44, v57 op_sel:[0,1,0] op_sel_hi:[0,1,0]
	v_fma_mix_f32 v14, v12, v75, v14 op_sel:[0,0,0] op_sel_hi:[0,1,0]
	v_fma_mix_f32 v57, v12, v45, v57 op_sel:[0,0,0] op_sel_hi:[0,1,0]
	v_fma_mix_f32 v14, v13, v75, v14 op_sel:[0,1,0] op_sel_hi:[0,1,0]
	v_fma_mix_f32 v16, v10, v72, 0 op_sel:[0,0,0] op_sel_hi:[0,1,0]
	v_fma_mix_f32 v17, v11, v72, 0 op_sel:[0,1,0] op_sel_hi:[0,1,0]
	v_add_f32_dpp v20, v14, v14 quad_perm:[1,0,3,2] row_mask:0xf bank_mask:0xf bound_ctrl:1
	v_fma_mix_f32 v57, v13, v45, v57 op_sel:[0,1,0] op_sel_hi:[0,1,0]
	v_fma_mix_f32 v18, v12, v73, 0 op_sel:[0,0,0] op_sel_hi:[0,1,0]
	v_add_f32_dpp v20, v20, v20 quad_perm:[2,3,0,1] row_mask:0xf bank_mask:0xf bound_ctrl:1
	v_fma_mix_f32 v19, v13, v73, 0 op_sel:[0,1,0] op_sel_hi:[0,1,0]
	v_fma_mix_f32 v16, v82, v78, v16 op_sel:[0,0,0] op_sel_hi:[1,1,0]
	v_add_f32_dpp v20, v20, v20 row_half_mirror row_mask:0xf bank_mask:0xf bound_ctrl:1
	v_fma_mix_f32 v17, v82, v78, v17 op_sel:[0,1,0] op_sel_hi:[1,1,0]
	v_fma_mix_f32 v18, v82, v79, v18 op_sel:[0,0,0] op_sel_hi:[1,1,0]
	v_add_f32_dpp v20, v20, v20 row_mirror row_mask:0xf bank_mask:0xf bound_ctrl:1
	v_fma_mix_f32 v19, v82, v79, v19 op_sel:[0,1,0] op_sel_hi:[1,1,0]
	v_fma_mix_f32 v10, v20, v76, v16 op_sel:[0,0,0] op_sel_hi:[0,1,0]
	v_fma_mix_f32 v11, v20, v76, v17 op_sel:[0,1,0] op_sel_hi:[0,1,0]
	v_fma_mix_f32 v12, v20, v77, v18 op_sel:[0,0,0] op_sel_hi:[0,1,0]
	v_fma_mix_f32 v13, v20, v77, v19 op_sel:[0,1,0] op_sel_hi:[0,1,0]
	s_waitcnt lgkmcnt(4)
	ds_read_b64 v[36:37], v6 offset:2072
	ds_read_b128 v[38:41], v6 offset:2320
	ds_read_b128 v[42:45], v6 offset:2576
	ds_read_u16 v46, v7 offset:2064
	v_fma_mix_f32 v14, v10, v86, 0 op_sel:[0,0,0] op_sel_hi:[0,1,0]
	v_fma_mix_f32 v58, v10, v80, 0 op_sel:[0,0,0] op_sel_hi:[0,1,0]
	v_fma_mix_f32 v14, v11, v86, v14 op_sel:[0,1,0] op_sel_hi:[0,1,0]
	v_fma_mix_f32 v58, v11, v80, v58 op_sel:[0,1,0] op_sel_hi:[0,1,0]
	v_fma_mix_f32 v14, v12, v87, v14 op_sel:[0,0,0] op_sel_hi:[0,1,0]
	v_fma_mix_f32 v58, v12, v81, v58 op_sel:[0,0,0] op_sel_hi:[0,1,0]
	v_fma_mix_f32 v14, v13, v87, v14 op_sel:[0,1,0] op_sel_hi:[0,1,0]
	v_fma_mix_f32 v16, v10, v84, 0 op_sel:[0,0,0] op_sel_hi:[0,1,0]
	v_fma_mix_f32 v17, v11, v84, 0 op_sel:[0,1,0] op_sel_hi:[0,1,0]
	v_add_f32_dpp v20, v14, v14 quad_perm:[1,0,3,2] row_mask:0xf bank_mask:0xf bound_ctrl:1
	v_fma_mix_f32 v58, v13, v81, v58 op_sel:[0,1,0] op_sel_hi:[0,1,0]
	v_fma_mix_f32 v18, v12, v85, 0 op_sel:[0,0,0] op_sel_hi:[0,1,0]
	v_add_f32_dpp v20, v20, v20 quad_perm:[2,3,0,1] row_mask:0xf bank_mask:0xf bound_ctrl:1
	v_fma_mix_f32 v19, v13, v85, 0 op_sel:[0,1,0] op_sel_hi:[0,1,0]
	v_fma_mix_f32 v16, v94, v90, v16 op_sel:[0,0,0] op_sel_hi:[1,1,0]
	v_add_f32_dpp v20, v20, v20 row_half_mirror row_mask:0xf bank_mask:0xf bound_ctrl:1
	v_fma_mix_f32 v17, v94, v90, v17 op_sel:[0,1,0] op_sel_hi:[1,1,0]
	v_fma_mix_f32 v18, v94, v91, v18 op_sel:[0,0,0] op_sel_hi:[1,1,0]
	v_add_f32_dpp v20, v20, v20 row_mirror row_mask:0xf bank_mask:0xf bound_ctrl:1
	v_fma_mix_f32 v19, v94, v91, v19 op_sel:[0,1,0] op_sel_hi:[1,1,0]
	v_fma_mix_f32 v10, v20, v88, v16 op_sel:[0,0,0] op_sel_hi:[0,1,0]
	v_fma_mix_f32 v11, v20, v88, v17 op_sel:[0,1,0] op_sel_hi:[0,1,0]
	v_fma_mix_f32 v12, v20, v89, v18 op_sel:[0,0,0] op_sel_hi:[0,1,0]
	v_fma_mix_f32 v13, v20, v89, v19 op_sel:[0,1,0] op_sel_hi:[0,1,0]
	s_waitcnt lgkmcnt(4)
	ds_read_b64 v[72:73], v6 offset:1048
	ds_read_b128 v[74:77], v6 offset:1296
	ds_read_b128 v[78:81], v6 offset:1552
	ds_read_u16 v82, v7 offset:1040
	v_fma_mix_f32 v14, v10, v26, 0 op_sel:[0,0,0] op_sel_hi:[0,1,0]
	v_fma_mix_f32 v59, v10, v92, 0 op_sel:[0,0,0] op_sel_hi:[0,1,0]
	v_fma_mix_f32 v14, v11, v26, v14 op_sel:[0,1,0] op_sel_hi:[0,1,0]
	v_fma_mix_f32 v59, v11, v92, v59 op_sel:[0,1,0] op_sel_hi:[0,1,0]
	v_fma_mix_f32 v14, v12, v27, v14 op_sel:[0,0,0] op_sel_hi:[0,1,0]
	v_fma_mix_f32 v59, v12, v93, v59 op_sel:[0,0,0] op_sel_hi:[0,1,0]
	v_fma_mix_f32 v14, v13, v27, v14 op_sel:[0,1,0] op_sel_hi:[0,1,0]
	v_fma_mix_f32 v16, v10, v24, 0 op_sel:[0,0,0] op_sel_hi:[0,1,0]
	v_fma_mix_f32 v17, v11, v24, 0 op_sel:[0,1,0] op_sel_hi:[0,1,0]
	v_add_f32_dpp v20, v14, v14 quad_perm:[1,0,3,2] row_mask:0xf bank_mask:0xf bound_ctrl:1
	v_fma_mix_f32 v59, v13, v93, v59 op_sel:[0,1,0] op_sel_hi:[0,1,0]
	v_fma_mix_f32 v18, v12, v25, 0 op_sel:[0,0,0] op_sel_hi:[0,1,0]
	v_add_f32_dpp v20, v20, v20 quad_perm:[2,3,0,1] row_mask:0xf bank_mask:0xf bound_ctrl:1
	v_fma_mix_f32 v19, v13, v25, 0 op_sel:[0,1,0] op_sel_hi:[0,1,0]
	v_fma_mix_f32 v16, v34, v30, v16 op_sel:[0,0,0] op_sel_hi:[1,1,0]
	v_add_f32_dpp v20, v20, v20 row_half_mirror row_mask:0xf bank_mask:0xf bound_ctrl:1
	v_fma_mix_f32 v17, v34, v30, v17 op_sel:[0,1,0] op_sel_hi:[1,1,0]
	v_fma_mix_f32 v18, v34, v31, v18 op_sel:[0,0,0] op_sel_hi:[1,1,0]
	v_add_f32_dpp v20, v20, v20 row_mirror row_mask:0xf bank_mask:0xf bound_ctrl:1
	v_fma_mix_f32 v19, v34, v31, v19 op_sel:[0,1,0] op_sel_hi:[1,1,0]
	v_fma_mix_f32 v10, v20, v28, v16 op_sel:[0,0,0] op_sel_hi:[0,1,0]
	v_fma_mix_f32 v11, v20, v28, v17 op_sel:[0,1,0] op_sel_hi:[0,1,0]
	v_fma_mix_f32 v12, v20, v29, v18 op_sel:[0,0,0] op_sel_hi:[0,1,0]
	v_fma_mix_f32 v13, v20, v29, v19 op_sel:[0,1,0] op_sel_hi:[0,1,0]
	s_waitcnt lgkmcnt(4)
; DEVINL u16 f2bf(float a) { return (u16)(pk2(a, 0.f) & 0xffffu); }
; #define RW_STEP2(B) RW_STEP(B, WvA, XA, KrA, vhA, WvB, XB, KrB, vhB); RW_STEP((B) + 1, WvB, XB, KrB, vhB, WvA, XA, KrA, vhA)
; #define RW_STEP4(B) RW_STEP2(B); RW_STEP2((B) + 2)
; template <int DIR>
; DEVINL void rwkv_scan_dir(const Params& p, int task, int lane, int wave) {
;     ...
; #pragma unroll 1
;   for (int st = 0; st < 4096; st += 32) {
;     RW_STEP(0, WvA, XA, KrA, vhA, WvB, XB, KrB, vhB);
;     if (st > 0) { const int q0 = st - 16 + seg; yo[(long)(DIR ? (4095 - q0) : q0) * 1024] = f2bf(ykeep); }
;     RW_STEP(1, WvB, XB, KrB, vhB, WvA, XA, KrA, vhA);
;     RW_STEP2(2); RW_STEP4(4); RW_STEP4(8); RW_STEP4(12);
;     RW_STEP(16, WvA, XA, KrA, vhA, WvB, XB, KrB, vhB);
;     { const int q0 = st + seg; yo[(long)(DIR ? (4095 - q0) : q0) * 1024] = f2bf(ykeep); }
;     RW_STEP(17, WvB, XB, KrB, vhB, WvA, XA, KrA, vhA);
;     RW_STEP2(18); RW_STEP4(20); RW_STEP4(24); RW_STEP4(28);
;   }
	ds_read_b64 v[84:85], v6 offset:24
	ds_read_b128 v[86:89], v6 offset:272
	ds_read_b128 v[90:93], v6 offset:528
	ds_read_u16 v94, v7 offset:16
	v_fma_mix_f32 v14, v10, v38, 0 op_sel:[0,0,0] op_sel_hi:[0,1,0]
	v_fma_mix_f32 v60, v10, v32, 0 op_sel:[0,0,0] op_sel_hi:[0,1,0]
	v_fma_mix_f32 v14, v11, v38, v14 op_sel:[0,1,0] op_sel_hi:[0,1,0]
	v_fma_mix_f32 v60, v11, v32, v60 op_sel:[0,1,0] op_sel_hi:[0,1,0]
	v_fma_mix_f32 v14, v12, v39, v14 op_sel:[0,0,0] op_sel_hi:[0,1,0]
	v_fma_mix_f32 v60, v12, v33, v60 op_sel:[0,0,0] op_sel_hi:[0,1,0]
	v_fma_mix_f32 v14, v13, v39, v14 op_sel:[0,1,0] op_sel_hi:[0,1,0]
	v_fma_mix_f32 v16, v10, v36, 0 op_sel:[0,0,0] op_sel_hi:[0,1,0]
	v_fma_mix_f32 v17, v11, v36, 0 op_sel:[0,1,0] op_sel_hi:[0,1,0]
	v_add_f32_dpp v20, v14, v14 quad_perm:[1,0,3,2] row_mask:0xf bank_mask:0xf bound_ctrl:1
	v_fma_mix_f32 v60, v13, v33, v60 op_sel:[0,1,0] op_sel_hi:[0,1,0]
	v_fma_mix_f32 v18, v12, v37, 0 op_sel:[0,0,0] op_sel_hi:[0,1,0]
	v_add_f32_dpp v20, v20, v20 quad_perm:[2,3,0,1] row_mask:0xf bank_mask:0xf bound_ctrl:1
	v_fma_mix_f32 v19, v13, v37, 0 op_sel:[0,1,0] op_sel_hi:[0,1,0]
	v_fma_mix_f32 v16, v46, v42, v16 op_sel:[0,0,0] op_sel_hi:[1,1,0]
	v_add_f32_dpp v20, v20, v20 row_half_mirror row_mask:0xf bank_mask:0xf bound_ctrl:1
	v_fma_mix_f32 v17, v46, v42, v17 op_sel:[0,1,0] op_sel_hi:[1,1,0]
	v_fma_mix_f32 v18, v46, v43, v18 op_sel:[0,0,0] op_sel_hi:[1,1,0]
	v_add_f32_dpp v20, v20, v20 row_mirror row_mask:0xf bank_mask:0xf bound_ctrl:1
	v_fma_mix_f32 v19, v46, v43, v19 op_sel:[0,1,0] op_sel_hi:[1,1,0]
	v_fma_mix_f32 v10, v20, v40, v16 op_sel:[0,0,0] op_sel_hi:[0,1,0]
	v_fma_mix_f32 v11, v20, v40, v17 op_sel:[0,1,0] op_sel_hi:[0,1,0]
	v_fma_mix_f32 v12, v20, v41, v18 op_sel:[0,0,0] op_sel_hi:[0,1,0]
	v_fma_mix_f32 v13, v20, v41, v19 op_sel:[0,1,0] op_sel_hi:[0,1,0]
	s_waitcnt lgkmcnt(4)
	v_add_u32_e32 v6, 0xffffc000, v6
	v_add_u32_e32 v7, 0xffffc000, v7
	v_and_b32_e32 v6, 0x1ffff, v6
	v_and_b32_e32 v7, 0x1ffff, v7
	ds_read_b64 v[24:25], v6 offset:15384
	ds_read_b128 v[26:29], v6 offset:15632
	ds_read_b128 v[30:33], v6 offset:15888
	ds_read_u16 v34, v7 offset:15376
	v_fma_mix_f32 v14, v10, v74, 0 op_sel:[0,0,0] op_sel_hi:[0,1,0]
	v_fma_mix_f32 v61, v10, v44, 0 op_sel:[0,0,0] op_sel_hi:[0,1,0]
	v_fma_mix_f32 v14, v11, v74, v14 op_sel:[0,1,0] op_sel_hi:[0,1,0]
	v_fma_mix_f32 v61, v11, v44, v61 op_sel:[0,1,0] op_sel_hi:[0,1,0]
	v_fma_mix_f32 v14, v12, v75, v14 op_sel:[0,0,0] op_sel_hi:[0,1,0]
	v_fma_mix_f32 v61, v12, v45, v61 op_sel:[0,0,0] op_sel_hi:[0,1,0]
	v_fma_mix_f32 v14, v13, v75, v14 op_sel:[0,1,0] op_sel_hi:[0,1,0]
	v_fma_mix_f32 v16, v10, v72, 0 op_sel:[0,0,0] op_sel_hi:[0,1,0]
	v_fma_mix_f32 v17, v11, v72, 0 op_sel:[0,1,0] op_sel_hi:[0,1,0]
	v_add_f32_dpp v20, v14, v14 quad_perm:[1,0,3,2] row_mask:0xf bank_mask:0xf bound_ctrl:1
	v_fma_mix_f32 v61, v13, v45, v61 op_sel:[0,1,0] op_sel_hi:[0,1,0]
	v_fma_mix_f32 v18, v12, v73, 0 op_sel:[0,0,0] op_sel_hi:[0,1,0]
	v_add_f32_dpp v20, v20, v20 quad_perm:[2,3,0,1] row_mask:0xf bank_mask:0xf bound_ctrl:1
	v_fma_mix_f32 v19, v13, v73, 0 op_sel:[0,1,0] op_sel_hi:[0,1,0]
	v_fma_mix_f32 v16, v82, v78, v16 op_sel:[0,0,0] op_sel_hi:[1,1,0]
	v_add_f32_dpp v20, v20, v20 row_half_mirror row_mask:0xf bank_mask:0xf bound_ctrl:1
	v_fma_mix_f32 v17, v82, v78, v17 op_sel:[0,1,0] op_sel_hi:[1,1,0]
	v_fma_mix_f32 v18, v82, v79, v18 op_sel:[0,0,0] op_sel_hi:[1,1,0]
	v_add_f32_dpp v20, v20, v20 row_mirror row_mask:0xf bank_mask:0xf bound_ctrl:1
	v_fma_mix_f32 v19, v82, v79, v19 op_sel:[0,1,0] op_sel_hi:[1,1,0]
	v_fma_mix_f32 v10, v20, v76, v16 op_sel:[0,0,0] op_sel_hi:[0,1,0]
	v_fma_mix_f32 v11, v20, v76, v17 op_sel:[0,1,0] op_sel_hi:[0,1,0]
	v_fma_mix_f32 v12, v20, v77, v18 op_sel:[0,0,0] op_sel_hi:[0,1,0]
	v_fma_mix_f32 v13, v20, v77, v19 op_sel:[0,1,0] op_sel_hi:[0,1,0]
	s_waitcnt lgkmcnt(4)
	ds_read_b64 v[36:37], v6 offset:14360
	ds_read_b128 v[38:41], v6 offset:14608
	ds_read_b128 v[42:45], v6 offset:14864
	ds_read_u16 v46, v7 offset:14352
	v_fma_mix_f32 v14, v10, v86, 0 op_sel:[0,0,0] op_sel_hi:[0,1,0]
	v_fma_mix_f32 v62, v10, v80, 0 op_sel:[0,0,0] op_sel_hi:[0,1,0]
	v_fma_mix_f32 v14, v11, v86, v14 op_sel:[0,1,0] op_sel_hi:[0,1,0]
	v_fma_mix_f32 v62, v11, v80, v62 op_sel:[0,1,0] op_sel_hi:[0,1,0]
	v_fma_mix_f32 v14, v12, v87, v14 op_sel:[0,0,0] op_sel_hi:[0,1,0]
	v_fma_mix_f32 v62, v12, v81, v62 op_sel:[0,0,0] op_sel_hi:[0,1,0]
	v_fma_mix_f32 v14, v13, v87, v14 op_sel:[0,1,0] op_sel_hi:[0,1,0]
	v_fma_mix_f32 v16, v10, v84, 0 op_sel:[0,0,0] op_sel_hi:[0,1,0]
	v_fma_mix_f32 v17, v11, v84, 0 op_sel:[0,1,0] op_sel_hi:[0,1,0]
	v_add_f32_dpp v20, v14, v14 quad_perm:[1,0,3,2] row_mask:0xf bank_mask:0xf bound_ctrl:1
	v_fma_mix_f32 v62, v13, v81, v62 op_sel:[0,1,0] op_sel_hi:[0,1,0]
	v_fma_mix_f32 v18, v12, v85, 0 op_sel:[0,0,0] op_sel_hi:[0,1,0]
	v_add_f32_dpp v20, v20, v20 quad_perm:[2,3,0,1] row_mask:0xf bank_mask:0xf bound_ctrl:1
	v_fma_mix_f32 v19, v13, v85, 0 op_sel:[0,1,0] op_sel_hi:[0,1,0]
	v_fma_mix_f32 v16, v94, v90, v16 op_sel:[0,0,0] op_sel_hi:[1,1,0]
	v_add_f32_dpp v20, v20, v20 row_half_mirror row_mask:0xf bank_mask:0xf bound_ctrl:1
	v_fma_mix_f32 v17, v94, v90, v17 op_sel:[0,1,0] op_sel_hi:[1,1,0]
	v_fma_mix_f32 v18, v94, v91, v18 op_sel:[0,0,0] op_sel_hi:[1,1,0]
	v_add_f32_dpp v20, v20, v20 row_mirror row_mask:0xf bank_mask:0xf bound_ctrl:1
	v_fma_mix_f32 v19, v94, v91, v19 op_sel:[0,1,0] op_sel_hi:[1,1,0]
	v_fma_mix_f32 v10, v20, v88, v16 op_sel:[0,0,0] op_sel_hi:[0,1,0]
	v_fma_mix_f32 v11, v20, v88, v17 op_sel:[0,1,0] op_sel_hi:[0,1,0]
	v_fma_mix_f32 v12, v20, v89, v18 op_sel:[0,0,0] op_sel_hi:[0,1,0]
	v_fma_mix_f32 v13, v20, v89, v19 op_sel:[0,1,0] op_sel_hi:[0,1,0]
	s_waitcnt lgkmcnt(4)
	s_add_u32 s15, s15, 1
	s_add_u32 s14, s14, 1
	v_mov_b32_e32 v69, s15
	ds_write_b32 v68, v69
	s_cmp_lt_u32 s14, 0x100
	s_cbranch_scc1 .Lrw_blk_d1
; DEVINL u16 f2bf(float a) { return (u16)(pk2(a, 0.f) & 0xffffu); }
; #define RW_STEP2(B) RW_STEP(B, WvA, XA, KrA, vhA, WvB, XB, KrB, vhB); RW_STEP((B) + 1, WvB, XB, KrB, vhB, WvA, XA, KrA, vhA)
; #define RW_STEP4(B) RW_STEP2(B); RW_STEP2((B) + 2)
; template <int DIR>
; DEVINL void rwkv_scan_dir(const Params& p, int task, int lane, int wave) {
;     ...
;     { const int q0 = st + seg; yo[(long)(DIR ? (4095 - q0) : q0) * 1024] = f2bf(ykeep); }
;     RW_STEP(17, WvB, XB, KrB, vhB, WvA, XA, KrA, vhA);
;     RW_STEP2(18); RW_STEP4(20); RW_STEP4(24); RW_STEP4(28);
;   }
;   {
;     const float ylast = allred16(ypart);
;     ykeep = (seg == 15) ? ylast : ykeep;
;     const int q0 = 4096 - 16 + seg; yo[(long)(DIR ? (4095 - q0) : q0) * 1024] = f2bf(ykeep);
;   }
	v_fma_mix_f32 v21, v10, v92, 0 op_sel:[0,0,0] op_sel_hi:[0,1,0]
	v_fma_mix_f32 v22, v12, v93, 0 op_sel:[0,0,0] op_sel_hi:[0,1,0]
	v_fma_mix_f32 v21, v11, v92, v21 op_sel:[0,1,0] op_sel_hi:[0,1,0]
	v_fma_mix_f32 v22, v13, v93, v22 op_sel:[0,1,0] op_sel_hi:[0,1,0]
	v_add_f32_e32 v63, v21, v22
	s_nop 1
	v_add_f32_dpp v48, v48, v48 row_ror:8 row_mask:0xf bank_mask:0x3
	v_add_f32_dpp v49, v49, v49 row_ror:8 row_mask:0xf bank_mask:0x3
	v_add_f32_dpp v50, v50, v50 row_ror:8 row_mask:0xf bank_mask:0x3
	v_add_f32_dpp v51, v51, v51 row_ror:8 row_mask:0xf bank_mask:0x3
	v_add_f32_dpp v52, v52, v52 row_ror:8 row_mask:0xf bank_mask:0x3
	v_add_f32_dpp v53, v53, v53 row_ror:8 row_mask:0xf bank_mask:0x3
	v_add_f32_dpp v54, v54, v54 row_ror:8 row_mask:0xf bank_mask:0x3
	v_add_f32_dpp v55, v55, v55 row_ror:8 row_mask:0xf bank_mask:0x3
	v_add_f32_dpp v48, v56, v56 row_ror:8 row_mask:0xf bank_mask:0xc
	v_add_f32_dpp v49, v57, v57 row_ror:8 row_mask:0xf bank_mask:0xc
	v_add_f32_dpp v50, v58, v58 row_ror:8 row_mask:0xf bank_mask:0xc
	v_add_f32_dpp v51, v59, v59 row_ror:8 row_mask:0xf bank_mask:0xc
	v_add_f32_dpp v52, v60, v60 row_ror:8 row_mask:0xf bank_mask:0xc
	v_add_f32_dpp v53, v61, v61 row_ror:8 row_mask:0xf bank_mask:0xc
	v_add_f32_dpp v54, v62, v62 row_ror:8 row_mask:0xf bank_mask:0xc
	v_add_f32_dpp v55, v63, v63 row_ror:8 row_mask:0xf bank_mask:0xc
	v_add_f32_dpp v48, v48, v48 row_ror:12 row_mask:0xf bank_mask:0x5
	v_add_f32_dpp v49, v49, v49 row_ror:12 row_mask:0xf bank_mask:0x5
	v_add_f32_dpp v50, v50, v50 row_ror:12 row_mask:0xf bank_mask:0x5
	v_add_f32_dpp v51, v51, v51 row_ror:12 row_mask:0xf bank_mask:0x5
	v_add_f32_dpp v48, v52, v52 row_ror:4 row_mask:0xf bank_mask:0xa
	v_add_f32_dpp v49, v53, v53 row_ror:4 row_mask:0xf bank_mask:0xa
	v_add_f32_dpp v50, v54, v54 row_ror:4 row_mask:0xf bank_mask:0xa
	v_add_f32_dpp v51, v55, v55 row_ror:4 row_mask:0xf bank_mask:0xa
	v_add_f32_dpp v64, v48, v48 quad_perm:[2,3,0,1] row_mask:0xf bank_mask:0xf bound_ctrl:1
	v_add_f32_dpp v65, v50, v50 quad_perm:[2,3,0,1] row_mask:0xf bank_mask:0xf bound_ctrl:1
	v_cndmask_b32_e64 v56, v64, v65, s[50:51]
	v_add_f32_dpp v64, v49, v49 quad_perm:[2,3,0,1] row_mask:0xf bank_mask:0xf bound_ctrl:1
	v_add_f32_dpp v65, v51, v51 quad_perm:[2,3,0,1] row_mask:0xf bank_mask:0xf bound_ctrl:1
	v_cndmask_b32_e64 v57, v64, v65, s[50:51]
	v_add_f32_dpp v64, v56, v56 quad_perm:[1,0,3,2] row_mask:0xf bank_mask:0xf bound_ctrl:1
	s_nop 0
	v_add_f32_dpp v65, v57, v57 quad_perm:[1,0,3,2] row_mask:0xf bank_mask:0xf bound_ctrl:1
	v_cndmask_b32_e64 v66, v64, v65, s[48:49]
	v_cvt_pk_bf16_f32 v66, v66, v66
	global_store_short v8, v66, s[12:13]
	s_sub_u32 s12, s12, 0x8000
	s_subb_u32 s13, s13, 0
